# v35 + scan_a_fast sub-chunk waits counted (vmcnt(10)) instead of draining
# baseline (speedup 1.0000x reference)
.LBB0_1160:
	s_and_b64 vcc, exec, s[6:7]
	s_barrier
	s_cbranch_vccnz .LBB0_1162
	s_waitcnt vmcnt(10)
	v_cvt_f32_f16_sdwa v135, v124 dst_sel:DWORD dst_unused:UNUSED_PAD src0_sel:WORD_1
	v_cvt_f32_f16_e32 v134, v124
	v_cvt_f32_f16_sdwa v137, v123 dst_sel:DWORD dst_unused:UNUSED_PAD src0_sel:WORD_1
	v_cvt_f32_f16_e32 v136, v123
	v_cvt_f32_f16_sdwa v123, v122 dst_sel:DWORD dst_unused:UNUSED_PAD src0_sel:WORD_1
	v_cvt_f32_f16_e32 v122, v122
	v_cvt_f32_f16_sdwa v139, v121 dst_sel:DWORD dst_unused:UNUSED_PAD src0_sel:WORD_1
	v_cvt_f32_f16_e32 v138, v121
	v_pk_add_f32 v[140:141], v[134:135], 0 op_sel_hi:[1,0]
	v_cvt_f32_f16_sdwa v149, v118 dst_sel:DWORD dst_unused:UNUSED_PAD src0_sel:WORD_1
	v_cvt_f32_f16_e32 v148, v118
	v_pk_add_f32 v[142:143], v[140:141], v[136:137]
	v_cvt_f32_f16_sdwa v151, v117 dst_sel:DWORD dst_unused:UNUSED_PAD src0_sel:WORD_1
	v_cvt_f32_f16_e32 v150, v117
	v_pk_add_f32 v[144:145], v[142:143], v[122:123]
	v_cvt_f32_f16_sdwa v117, v116 dst_sel:DWORD dst_unused:UNUSED_PAD src0_sel:WORD_1
	v_cvt_f32_f16_e32 v116, v116
	v_pk_add_f32 v[146:147], v[144:145], v[138:139]
	v_cvt_f32_f16_sdwa v153, v115 dst_sel:DWORD dst_unused:UNUSED_PAD src0_sel:WORD_1
	v_cvt_f32_f16_e32 v152, v115
	v_pk_add_f32 v[154:155], v[146:147], v[148:149]
	v_and_or_b32 v2, v1, 64, v85
	v_pk_add_f32 v[156:157], v[154:155], v[150:151]
	v_lshlrev_b32_e32 v2, 2, v2
	v_pk_add_f32 v[158:159], v[156:157], v[116:117]
	v_exp_f32_e32 v134, v134
	v_pk_add_f32 v[160:161], v[158:159], v[152:153]
	ds_bpermute_b32 v94, v2, v160
	ds_bpermute_b32 v95, v2, v161
	ds_bpermute_b32 v162, v2, v160 offset:64
	ds_bpermute_b32 v163, v2, v161 offset:64
	ds_bpermute_b32 v164, v2, v160 offset:128
	ds_bpermute_b32 v165, v2, v161 offset:128
	ds_bpermute_b32 v166, v2, v160 offset:192
	ds_bpermute_b32 v167, v2, v161 offset:192
	s_waitcnt lgkmcnt(6)
	v_cndmask_b32_e64 v169, 0, v95, s[12:13]
	v_cndmask_b32_e64 v168, 0, v94, s[12:13]
	s_waitcnt lgkmcnt(4)
	v_cndmask_b32_e64 v171, 0, v163, s[10:11]
	v_cndmask_b32_e64 v170, 0, v162, s[10:11]
	v_pk_add_f32 v[168:169], v[168:169], v[170:171]
	s_waitcnt lgkmcnt(2)
	v_cndmask_b32_e64 v171, 0, v165, s[8:9]
	v_cndmask_b32_e64 v170, 0, v164, s[8:9]
	v_pk_add_f32 v[94:95], v[94:95], v[162:163]
	s_waitcnt lgkmcnt(0)
	v_pk_add_f32 v[162:163], v[164:165], v[166:167]
	v_pk_add_f32 v[168:169], v[168:169], v[170:171]
	v_pk_add_f32 v[94:95], v[94:95], v[162:163]
	v_exp_f32_e32 v135, v135
	v_pk_add_f32 v[162:163], v[94:95], v[168:169] neg_lo:[0,1] neg_hi:[0,1]
	ds_write_b128 v100, v[72:75] offset:30720
	ds_write_b128 v100, v[68:71] offset:30736
	v_pk_add_f32 v[162:163], v[86:87], v[162:163]
	v_pk_add_f32 v[68:69], v[134:135], 1.0 op_sel_hi:[1,0] neg_lo:[1,0] neg_hi:[1,0]
	v_pk_add_f32 v[140:141], v[162:163], v[140:141] neg_lo:[0,1] neg_hi:[0,1]
	v_exp_f32_e32 v70, v136
	v_exp_f32_e32 v140, v140
	v_exp_f32_e32 v141, v141
	v_exp_f32_e32 v71, v137
	v_mad_u64_u32 v[72:73], s[16:17], v96, s15, v[90:91]
	v_pk_mul_f32 v[68:69], v[68:69], v[140:141]
	v_pk_add_f32 v[70:71], v[70:71], 1.0 op_sel_hi:[1,0] neg_lo:[1,0] neg_hi:[1,0]
	v_cvt_pk_bf16_f32 v2, v68, v69
	v_pk_add_f32 v[68:69], v[162:163], v[142:143] neg_lo:[0,1] neg_hi:[0,1]
	v_add_u32_e32 v73, 0x5000, v72
	v_exp_f32_e32 v68, v68
	v_exp_f32_e32 v69, v69
	v_pk_add_f32 v[74:75], v[162:163], v[146:147] neg_lo:[0,1] neg_hi:[0,1]
	s_and_b64 s[16:17], s[4:5], exec
	v_exp_f32_e32 v74, v74
	v_pk_mul_f32 v[68:69], v[70:71], v[68:69]
	v_exp_f32_e32 v75, v75
	v_cvt_pk_bf16_f32 v70, v68, v69
	v_exp_f32_e32 v68, v122
	v_exp_f32_e32 v69, v123
	ds_write2_b32 v73, v2, v70 offset1:80
	v_pk_add_f32 v[70:71], v[162:163], v[144:145] neg_lo:[0,1] neg_hi:[0,1]
	v_exp_f32_e32 v122, v138
	v_exp_f32_e32 v70, v70
	v_exp_f32_e32 v71, v71
	v_exp_f32_e32 v123, v139
	v_pk_add_f32 v[68:69], v[68:69], 1.0 op_sel_hi:[1,0] neg_lo:[1,0] neg_hi:[1,0]
	s_cselect_b32 s2, 64, 0xa0
	v_pk_mul_f32 v[68:69], v[68:69], v[70:71]
	v_exp_f32_e32 v70, v148
	v_cvt_pk_bf16_f32 v2, v68, v69
	v_pk_add_f32 v[68:69], v[122:123], 1.0 op_sel_hi:[1,0] neg_lo:[1,0] neg_hi:[1,0]
	v_exp_f32_e32 v71, v149
	v_pk_mul_f32 v[68:69], v[68:69], v[74:75]
	v_pk_add_f32 v[74:75], v[162:163], v[156:157] neg_lo:[0,1] neg_hi:[0,1]
	v_cvt_pk_bf16_f32 v68, v68, v69
	ds_write2_b32 v73, v2, v68 offset0:160 offset1:240
	v_pk_add_f32 v[68:69], v[162:163], v[154:155] neg_lo:[0,1] neg_hi:[0,1]
	v_exp_f32_e32 v122, v150
	v_exp_f32_e32 v68, v68
	v_exp_f32_e32 v69, v69
	v_exp_f32_e32 v123, v151
	v_exp_f32_e32 v74, v74
	v_exp_f32_e32 v75, v75
	v_pk_add_f32 v[70:71], v[70:71], 1.0 op_sel_hi:[1,0] neg_lo:[1,0] neg_hi:[1,0]
	v_pk_add_f32 v[86:87], v[86:87], v[94:95]
	v_pk_mul_f32 v[68:69], v[70:71], v[68:69]
	v_add_u32_e32 v71, 0x5400, v72
	v_cvt_pk_bf16_f32 v2, v68, v69
	v_pk_add_f32 v[68:69], v[122:123], 1.0 op_sel_hi:[1,0] neg_lo:[1,0] neg_hi:[1,0]
	s_nop 0
	v_pk_mul_f32 v[68:69], v[68:69], v[74:75]
	v_pk_add_f32 v[74:75], v[162:163], v[160:161] neg_lo:[0,1] neg_hi:[0,1]
	v_cvt_pk_bf16_f32 v70, v68, v69
	v_exp_f32_e32 v68, v116
	v_exp_f32_e32 v69, v117
	ds_write2_b32 v71, v2, v70 offset0:64 offset1:144
	v_pk_add_f32 v[70:71], v[162:163], v[158:159] neg_lo:[0,1] neg_hi:[0,1]
	v_exp_f32_e32 v116, v152
	v_exp_f32_e32 v70, v70
	v_exp_f32_e32 v71, v71
	v_exp_f32_e32 v117, v153
	v_exp_f32_e32 v74, v74
	v_exp_f32_e32 v75, v75
	v_pk_add_f32 v[68:69], v[68:69], 1.0 op_sel_hi:[1,0] neg_lo:[1,0] neg_hi:[1,0]
	s_nop 0
	v_pk_mul_f32 v[68:69], v[68:69], v[70:71]
	s_nop 0
	v_cvt_pk_bf16_f32 v2, v68, v69
	v_pk_add_f32 v[68:69], v[116:117], 1.0 op_sel_hi:[1,0] neg_lo:[1,0] neg_hi:[1,0]
	s_nop 0
	v_pk_mul_f32 v[68:69], v[68:69], v[74:75]
	s_nop 0
	v_cvt_pk_bf16_f32 v68, v68, v69
	v_add_u32_e32 v69, 0x5600, v72
	ds_write2_b32 v69, v2, v68 offset0:96 offset1:176
	v_add_u32_e32 v68, s2, v101
	v_ashrrev_i32_e32 v69, 31, v68
	v_lshlrev_b64 v[68:69], 11, v[68:69]
	v_lshl_add_u64 v[68:69], s[20:21], 0, v[68:69]
	v_lshl_add_u64 v[68:69], s[38:39], 1, v[68:69]
	v_lshl_add_u64 v[72:73], v[88:89], 1, v[68:69]
	global_load_dwordx4 v[68:71], v[72:73], off offset:16
	s_nop 0
	global_load_dwordx4 v[72:75], v[72:73], off
	s_or_b32 s2, s66, s2
	v_cndmask_b32_e64 v2, v120, v119, s[4:5]
	ds_read_b64_tr_b16 v[134:135], v97 offset:10240
	ds_read_b64_tr_b16 v[136:137], v97 offset:11520
	ds_read_b64_tr_b16 v[138:139], v97 offset:15360
	ds_read_b64_tr_b16 v[140:141], v97 offset:16640
	v_add_u32_e32 v116, s2, v2
	v_add3_u32 v2, s65, v99, v98
	ds_read_b64_tr_b16 v[142:143], v2
	ds_read_b64_tr_b16 v[144:145], v2 offset:1280
	ds_read_b64_tr_b16 v[146:147], v2 offset:5120
	ds_read_b64_tr_b16 v[148:149], v2 offset:6400
	ds_read_b64_tr_b16 v[150:151], v2 offset:64
	ds_read_b64_tr_b16 v[154:155], v2 offset:128
	ds_read_b64_tr_b16 v[158:159], v2 offset:192
	ds_read_b64_tr_b16 v[152:153], v2 offset:1344
	ds_read_b64_tr_b16 v[156:157], v2 offset:1408
	ds_read_b64_tr_b16 v[160:161], v2 offset:1472
	s_waitcnt lgkmcnt(8)
	v_mfma_f32_32x32x16_bf16 v[52:67], v[142:145], v[134:137], v[52:67]
	ds_read_b64_tr_b16 v[142:143], v2 offset:5184
	ds_read_b64_tr_b16 v[162:163], v2 offset:5248
	ds_read_b64_tr_b16 v[166:167], v2 offset:5312
	ds_read_b64_tr_b16 v[144:145], v2 offset:6464
	ds_read_b64_tr_b16 v[164:165], v2 offset:6528
	ds_read_b64_tr_b16 v[168:169], v2 offset:6592
	v_cndmask_b32_e64 v2, v114, v112, s[4:5]
	v_add_u32_e32 v122, s2, v2
	v_cndmask_b32_e64 v2, v113, v110, s[4:5]
	v_ashrrev_i32_e32 v117, 31, v116
	v_ashrrev_i32_e32 v123, 31, v122
	v_lshlrev_b64 v[116:117], 11, v[116:117]
	s_waitcnt lgkmcnt(8)
	v_mfma_f32_32x32x16_bf16 v[36:51], v[150:153], v[134:137], v[36:51]
	v_add_u32_e32 v152, s2, v104
	v_lshlrev_b64 v[122:123], 11, v[122:123]
	v_ashrrev_i32_e32 v153, 31, v152
	v_lshl_add_u64 v[116:117], v[92:93], 0, v[116:117]
	v_lshl_add_u64 v[122:123], v[92:93], 0, v[122:123]
	v_lshlrev_b64 v[152:153], 11, v[152:153]
	v_lshl_add_u64 v[152:153], v[92:93], 0, v[152:153]
	v_mfma_f32_32x32x16_bf16 v[52:67], v[146:149], v[138:141], v[52:67]
	v_add_u32_e32 v146, s2, v2
	v_cndmask_b32_e64 v2, v111, v107, s[4:5]
	v_add_u32_e32 v148, s2, v2
	v_cndmask_b32_e64 v2, v109, v105, s[4:5]
	v_ashrrev_i32_e32 v149, 31, v148
	v_ashrrev_i32_e32 v147, 31, v146
	v_lshlrev_b64 v[146:147], 11, v[146:147]
	s_waitcnt lgkmcnt(2)
	v_mfma_f32_32x32x16_bf16 v[36:51], v[142:145], v[138:141], v[36:51]
	v_add_u32_e32 v144, s2, v2
	v_cndmask_b32_e64 v2, v108, v103, s[4:5]
	v_lshlrev_b64 v[142:143], 11, v[148:149]
	v_add_u32_e32 v148, s2, v2
	v_cndmask_b32_e64 v2, v106, v102, s[4:5]
	v_add_u32_e32 v150, s2, v2
	v_ashrrev_i32_e32 v145, 31, v144
	v_ashrrev_i32_e32 v149, 31, v148
	v_ashrrev_i32_e32 v151, 31, v150
	v_lshlrev_b64 v[144:145], 11, v[144:145]
	v_lshlrev_b64 v[148:149], 11, v[148:149]
	v_lshlrev_b64 v[150:151], 11, v[150:151]
	v_lshl_add_u64 v[146:147], v[92:93], 0, v[146:147]
	v_lshl_add_u64 v[142:143], v[92:93], 0, v[142:143]
	v_lshl_add_u64 v[144:145], v[92:93], 0, v[144:145]
	v_lshl_add_u64 v[148:149], v[92:93], 0, v[148:149]
	v_lshl_add_u64 v[150:151], v[92:93], 0, v[150:151]
	global_load_dword v115, v[116:117], off
	s_nop 0
	global_load_dword v116, v[122:123], off
	global_load_dword v117, v[146:147], off
	global_load_dword v118, v[142:143], off
	global_load_dword v121, v[144:145], off
	s_nop 0
	global_load_dword v122, v[148:149], off
	global_load_dword v123, v[150:151], off
	global_load_dword v124, v[152:153], off
	v_mfma_f32_32x32x16_bf16 v[20:35], v[154:157], v[134:137], v[20:35]
	v_mfma_f32_32x32x16_bf16 v[4:19], v[158:161], v[134:137], v[4:19]
	s_waitcnt lgkmcnt(1)
	v_mfma_f32_32x32x16_bf16 v[20:35], v[162:165], v[138:141], v[20:35]
	s_waitcnt lgkmcnt(0)
	v_mfma_f32_32x32x16_bf16 v[4:19], v[166:169], v[138:141], v[4:19]
.LBB0_1162:
	s_and_b64 vcc, exec, s[6:7]
	s_barrier
	s_cbranch_vccnz .LBB0_1164
	s_waitcnt vmcnt(10)
	v_cvt_f32_f16_sdwa v133, v132 dst_sel:DWORD dst_unused:UNUSED_PAD src0_sel:WORD_1
	v_cvt_f32_f16_e32 v132, v132
	s_waitcnt vmcnt(10)
	v_cvt_f32_f16_sdwa v135, v131 dst_sel:DWORD dst_unused:UNUSED_PAD src0_sel:WORD_1
	v_cvt_f32_f16_e32 v134, v131
	s_waitcnt vmcnt(10)
	v_cvt_f32_f16_sdwa v131, v130 dst_sel:DWORD dst_unused:UNUSED_PAD src0_sel:WORD_1
	v_cvt_f32_f16_e32 v130, v130
	s_waitcnt vmcnt(10)
	v_cvt_f32_f16_sdwa v137, v129 dst_sel:DWORD dst_unused:UNUSED_PAD src0_sel:WORD_1
	v_cvt_f32_f16_e32 v136, v129
	v_pk_add_f32 v[138:139], v[132:133], 0 op_sel_hi:[1,0]
	s_waitcnt vmcnt(10)
	v_cvt_f32_f16_sdwa v129, v128 dst_sel:DWORD dst_unused:UNUSED_PAD src0_sel:WORD_1
	v_cvt_f32_f16_e32 v128, v128
	v_pk_add_f32 v[140:141], v[138:139], v[134:135]
	s_waitcnt vmcnt(10)
	v_cvt_f32_f16_sdwa v147, v127 dst_sel:DWORD dst_unused:UNUSED_PAD src0_sel:WORD_1
	v_cvt_f32_f16_e32 v146, v127
	v_pk_add_f32 v[142:143], v[140:141], v[130:131]
	s_waitcnt vmcnt(10)
	v_cvt_f32_f16_sdwa v127, v126 dst_sel:DWORD dst_unused:UNUSED_PAD src0_sel:WORD_1
	v_cvt_f32_f16_e32 v126, v126
	v_pk_add_f32 v[144:145], v[142:143], v[136:137]
	s_waitcnt vmcnt(10)
	v_cvt_f32_f16_sdwa v149, v125 dst_sel:DWORD dst_unused:UNUSED_PAD src0_sel:WORD_1
	v_cvt_f32_f16_e32 v148, v125
	v_pk_add_f32 v[150:151], v[144:145], v[128:129]
	v_and_or_b32 v2, v1, 64, v85
	v_pk_add_f32 v[152:153], v[150:151], v[146:147]
	v_lshlrev_b32_e32 v2, 2, v2
	v_pk_add_f32 v[154:155], v[152:153], v[126:127]
	v_exp_f32_e32 v132, v132
	v_pk_add_f32 v[156:157], v[154:155], v[148:149]
	ds_bpermute_b32 v94, v2, v156
	ds_bpermute_b32 v95, v2, v157
	ds_bpermute_b32 v158, v2, v156 offset:64
	ds_bpermute_b32 v159, v2, v157 offset:64
	ds_bpermute_b32 v160, v2, v156 offset:128
	ds_bpermute_b32 v161, v2, v157 offset:128
	ds_bpermute_b32 v162, v2, v156 offset:192
	ds_bpermute_b32 v163, v2, v157 offset:192
	s_waitcnt lgkmcnt(6)
	v_cndmask_b32_e64 v165, 0, v95, s[12:13]
	v_cndmask_b32_e64 v164, 0, v94, s[12:13]
	s_waitcnt lgkmcnt(4)
	v_cndmask_b32_e64 v167, 0, v159, s[10:11]
	v_cndmask_b32_e64 v166, 0, v158, s[10:11]
	v_pk_add_f32 v[164:165], v[164:165], v[166:167]
	s_waitcnt lgkmcnt(2)
	v_cndmask_b32_e64 v167, 0, v161, s[8:9]
	v_cndmask_b32_e64 v166, 0, v160, s[8:9]
	v_pk_add_f32 v[94:95], v[94:95], v[158:159]
	s_waitcnt lgkmcnt(0)
	v_pk_add_f32 v[158:159], v[160:161], v[162:163]
	v_pk_add_f32 v[164:165], v[164:165], v[166:167]
	v_pk_add_f32 v[94:95], v[94:95], v[158:159]
	v_exp_f32_e32 v133, v133
	v_pk_add_f32 v[158:159], v[94:95], v[164:165] neg_lo:[0,1] neg_hi:[0,1]
	s_waitcnt vmcnt(10)
	ds_write_b128 v100, v[80:83] offset:10240
	ds_write_b128 v100, v[76:79] offset:10256
	v_pk_add_f32 v[158:159], v[86:87], v[158:159]
	v_pk_add_f32 v[76:77], v[132:133], 1.0 op_sel_hi:[1,0] neg_lo:[1,0] neg_hi:[1,0]
	v_pk_add_f32 v[138:139], v[158:159], v[138:139] neg_lo:[0,1] neg_hi:[0,1]
	v_exp_f32_e32 v78, v134
	v_exp_f32_e32 v138, v138
	v_exp_f32_e32 v139, v139
	v_exp_f32_e32 v79, v135
	v_mad_u64_u32 v[80:81], s[16:17], v96, s15, v[90:91]
	v_pk_mul_f32 v[76:77], v[76:77], v[138:139]
	v_pk_add_f32 v[78:79], v[78:79], 1.0 op_sel_hi:[1,0] neg_lo:[1,0] neg_hi:[1,0]
	v_cvt_pk_bf16_f32 v2, v76, v77
	v_pk_add_f32 v[76:77], v[158:159], v[140:141] neg_lo:[0,1] neg_hi:[0,1]
	v_pk_add_f32 v[82:83], v[158:159], v[144:145] neg_lo:[0,1] neg_hi:[0,1]
	v_exp_f32_e32 v76, v76
	v_exp_f32_e32 v77, v77
	v_exp_f32_e32 v82, v82
	v_exp_f32_e32 v83, v83
	s_and_b64 s[16:17], s[4:5], exec
	v_pk_mul_f32 v[76:77], v[78:79], v[76:77]
	v_exp_f32_e32 v78, v130
	v_cvt_pk_bf16_f32 v76, v76, v77
	v_exp_f32_e32 v79, v131
	ds_write2_b32 v80, v2, v76 offset1:80
	v_pk_add_f32 v[76:77], v[158:159], v[142:143] neg_lo:[0,1] neg_hi:[0,1]
	v_exp_f32_e32 v130, v136
	v_exp_f32_e32 v76, v76
	v_exp_f32_e32 v77, v77
	v_exp_f32_e32 v131, v137
	v_pk_add_f32 v[78:79], v[78:79], 1.0 op_sel_hi:[1,0] neg_lo:[1,0] neg_hi:[1,0]
	s_cselect_b32 s2, 32, 0xc0
	v_pk_mul_f32 v[76:77], v[78:79], v[76:77]
	v_exp_f32_e32 v78, v128
	v_cvt_pk_bf16_f32 v2, v76, v77
	v_pk_add_f32 v[76:77], v[130:131], 1.0 op_sel_hi:[1,0] neg_lo:[1,0] neg_hi:[1,0]
	v_exp_f32_e32 v79, v129
	v_pk_mul_f32 v[76:77], v[76:77], v[82:83]
	v_pk_add_f32 v[82:83], v[158:159], v[152:153] neg_lo:[0,1] neg_hi:[0,1]
	v_cvt_pk_bf16_f32 v76, v76, v77
	ds_write2_b32 v80, v2, v76 offset0:160 offset1:240
	v_pk_add_f32 v[76:77], v[158:159], v[150:151] neg_lo:[0,1] neg_hi:[0,1]
	v_exp_f32_e32 v128, v146
	v_exp_f32_e32 v76, v76
	v_exp_f32_e32 v77, v77
	v_exp_f32_e32 v129, v147
	v_exp_f32_e32 v82, v82
	v_exp_f32_e32 v83, v83
	v_pk_add_f32 v[78:79], v[78:79], 1.0 op_sel_hi:[1,0] neg_lo:[1,0] neg_hi:[1,0]
	s_or_b32 s16, s66, s2
	v_pk_mul_f32 v[76:77], v[78:79], v[76:77]
	v_add_u32_e32 v79, 0x400, v80
	v_cvt_pk_bf16_f32 v2, v76, v77
	v_pk_add_f32 v[76:77], v[128:129], 1.0 op_sel_hi:[1,0] neg_lo:[1,0] neg_hi:[1,0]
	v_add3_u32 v125, s65, v99, v98
	v_pk_mul_f32 v[76:77], v[76:77], v[82:83]
	v_pk_add_f32 v[82:83], v[158:159], v[156:157] neg_lo:[0,1] neg_hi:[0,1]
	v_cvt_pk_bf16_f32 v78, v76, v77
	v_exp_f32_e32 v76, v126
	v_exp_f32_e32 v77, v127
	ds_write2_b32 v79, v2, v78 offset0:64 offset1:144
	v_pk_add_f32 v[78:79], v[158:159], v[154:155] neg_lo:[0,1] neg_hi:[0,1]
	v_exp_f32_e32 v126, v148
	v_exp_f32_e32 v78, v78
	v_exp_f32_e32 v79, v79
	v_exp_f32_e32 v127, v149
	v_exp_f32_e32 v82, v82
	v_exp_f32_e32 v83, v83
	v_pk_add_f32 v[76:77], v[76:77], 1.0 op_sel_hi:[1,0] neg_lo:[1,0] neg_hi:[1,0]
	v_pk_add_f32 v[86:87], v[86:87], v[94:95]
	v_pk_mul_f32 v[76:77], v[76:77], v[78:79]
	s_nop 0
	v_cvt_pk_bf16_f32 v2, v76, v77
	v_pk_add_f32 v[76:77], v[126:127], 1.0 op_sel_hi:[1,0] neg_lo:[1,0] neg_hi:[1,0]
	s_nop 0
	v_pk_mul_f32 v[76:77], v[76:77], v[82:83]
	s_nop 0
	v_cvt_pk_bf16_f32 v76, v76, v77
	v_add_u32_e32 v77, 0x600, v80
	ds_write2_b32 v77, v2, v76 offset0:96 offset1:176
	v_add_u32_e32 v76, s16, v104
	v_ashrrev_i32_e32 v77, 31, v76
	v_lshlrev_b64 v[76:77], 11, v[76:77]
	v_cndmask_b32_e64 v2, v106, v102, s[4:5]
	v_lshl_add_u64 v[154:155], v[92:93], 0, v[76:77]
	v_add_u32_e32 v76, s16, v2
	v_ashrrev_i32_e32 v77, 31, v76
	v_lshlrev_b64 v[76:77], 11, v[76:77]
	v_lshl_add_u64 v[156:157], v[92:93], 0, v[76:77]
	ds_read_b64_tr_b16 v[76:77], v97 offset:30720
	ds_read_b64_tr_b16 v[78:79], v97 offset:32000
	ds_read_b64_tr_b16 v[134:135], v97 offset:35840
	ds_read_b64_tr_b16 v[136:137], v97 offset:37120
	ds_read_b64_tr_b16 v[80:81], v125 offset:20480
	ds_read_b64_tr_b16 v[82:83], v125 offset:21760
	ds_read_b64_tr_b16 v[126:127], v125 offset:25600
	ds_read_b64_tr_b16 v[128:129], v125 offset:26880
	ds_read_b64_tr_b16 v[130:131], v125 offset:20544
	ds_read_b64_tr_b16 v[138:139], v125 offset:20608
	ds_read_b64_tr_b16 v[142:143], v125 offset:20672
	ds_read_b64_tr_b16 v[132:133], v125 offset:21824
	ds_read_b64_tr_b16 v[140:141], v125 offset:21888
	ds_read_b64_tr_b16 v[144:145], v125 offset:21952
	s_waitcnt lgkmcnt(8)
	v_mfma_f32_32x32x16_bf16 v[52:67], v[80:83], v[76:79], v[52:67]
	v_cndmask_b32_e64 v2, v108, v103, s[4:5]
	v_add_u32_e32 v158, s16, v2
	ds_read_b64_tr_b16 v[80:81], v125 offset:25664
	ds_read_b64_tr_b16 v[146:147], v125 offset:25728
	ds_read_b64_tr_b16 v[150:151], v125 offset:25792
	ds_read_b64_tr_b16 v[82:83], v125 offset:26944
	ds_read_b64_tr_b16 v[148:149], v125 offset:27008
	ds_read_b64_tr_b16 v[152:153], v125 offset:27072
	v_cndmask_b32_e64 v2, v109, v105, s[4:5]
	v_ashrrev_i32_e32 v159, 31, v158
	s_waitcnt lgkmcnt(8)
	v_mfma_f32_32x32x16_bf16 v[36:51], v[130:133], v[76:79], v[36:51]
	v_mfma_f32_32x32x16_bf16 v[52:67], v[126:129], v[134:137], v[52:67]
	v_add_u32_e32 v128, s16, v2
	v_cndmask_b32_e64 v2, v111, v107, s[4:5]
	v_add_u32_e32 v130, s16, v2
	v_cndmask_b32_e64 v2, v113, v110, s[4:5]
	v_ashrrev_i32_e32 v131, 31, v130
	v_lshlrev_b64 v[130:131], 11, v[130:131]
	v_lshlrev_b64 v[126:127], 11, v[158:159]
	s_waitcnt lgkmcnt(2)
	v_mfma_f32_32x32x16_bf16 v[36:51], v[80:83], v[134:137], v[36:51]
	v_add_u32_e32 v80, s16, v2
	v_cndmask_b32_e64 v2, v114, v112, s[4:5]
	v_add_u32_e32 v82, s16, v2
	v_cndmask_b32_e64 v2, v120, v119, s[4:5]
	v_ashrrev_i32_e32 v129, 31, v128
	v_lshl_add_u64 v[158:159], v[92:93], 0, v[130:131]
	v_ashrrev_i32_e32 v81, 31, v80
	v_add_u32_e32 v130, s16, v2
	v_lshlrev_b64 v[128:129], 11, v[128:129]
	v_lshlrev_b64 v[80:81], 11, v[80:81]
	v_ashrrev_i32_e32 v83, 31, v82
	v_ashrrev_i32_e32 v131, 31, v130
	v_lshl_add_u64 v[126:127], v[92:93], 0, v[126:127]
	v_lshl_add_u64 v[128:129], v[92:93], 0, v[128:129]
	v_lshl_add_u64 v[80:81], v[92:93], 0, v[80:81]
	v_lshlrev_b64 v[82:83], 11, v[82:83]
	v_lshlrev_b64 v[130:131], 11, v[130:131]
	v_mfma_f32_32x32x16_bf16 v[20:35], v[138:141], v[76:79], v[20:35]
	v_lshl_add_u64 v[82:83], v[92:93], 0, v[82:83]
	v_lshl_add_u64 v[138:139], v[92:93], 0, v[130:131]
	global_load_dword v132, v[154:155], off
	global_load_dword v131, v[156:157], off
	global_load_dword v130, v[126:127], off
	s_nop 0
	global_load_dword v129, v[128:129], off
	s_nop 0
	global_load_dword v128, v[158:159], off
	global_load_dword v127, v[80:81], off
	global_load_dword v126, v[82:83], off
	global_load_dword v125, v[138:139], off
	v_add_u32_e32 v80, s2, v101
	v_ashrrev_i32_e32 v81, 31, v80
	v_lshlrev_b64 v[80:81], 11, v[80:81]
	v_lshl_add_u64 v[80:81], s[20:21], 0, v[80:81]
	v_lshl_add_u64 v[80:81], s[38:39], 1, v[80:81]
	v_lshl_add_u64 v[80:81], v[88:89], 1, v[80:81]
	v_mfma_f32_32x32x16_bf16 v[4:19], v[142:145], v[76:79], v[4:19]
	global_load_dwordx4 v[76:79], v[80:81], off offset:16
	s_nop 0
	global_load_dwordx4 v[80:83], v[80:81], off
	s_waitcnt lgkmcnt(1)
	v_mfma_f32_32x32x16_bf16 v[20:35], v[146:149], v[134:137], v[20:35]
	s_waitcnt lgkmcnt(0)
	v_mfma_f32_32x32x16_bf16 v[4:19], v[150:153], v[134:137], v[4:19]
.LBB0_1164:
	s_and_b64 vcc, exec, s[6:7]
	s_barrier
	s_cbranch_vccnz .LBB0_1166
	s_waitcnt vmcnt(10)
	v_cvt_f32_f16_sdwa v135, v124 dst_sel:DWORD dst_unused:UNUSED_PAD src0_sel:WORD_1
	v_cvt_f32_f16_e32 v134, v124
	v_cvt_f32_f16_sdwa v137, v123 dst_sel:DWORD dst_unused:UNUSED_PAD src0_sel:WORD_1
	v_cvt_f32_f16_e32 v136, v123
	v_cvt_f32_f16_sdwa v123, v122 dst_sel:DWORD dst_unused:UNUSED_PAD src0_sel:WORD_1
	v_cvt_f32_f16_e32 v122, v122
	v_cvt_f32_f16_sdwa v139, v121 dst_sel:DWORD dst_unused:UNUSED_PAD src0_sel:WORD_1
	v_cvt_f32_f16_e32 v138, v121
	v_pk_add_f32 v[140:141], v[134:135], 0 op_sel_hi:[1,0]
	v_cvt_f32_f16_sdwa v149, v118 dst_sel:DWORD dst_unused:UNUSED_PAD src0_sel:WORD_1
	v_cvt_f32_f16_e32 v148, v118
	v_pk_add_f32 v[142:143], v[140:141], v[136:137]
	v_cvt_f32_f16_sdwa v151, v117 dst_sel:DWORD dst_unused:UNUSED_PAD src0_sel:WORD_1
	v_cvt_f32_f16_e32 v150, v117
	v_pk_add_f32 v[144:145], v[142:143], v[122:123]
	v_cvt_f32_f16_sdwa v117, v116 dst_sel:DWORD dst_unused:UNUSED_PAD src0_sel:WORD_1
	v_cvt_f32_f16_e32 v116, v116
	v_pk_add_f32 v[146:147], v[144:145], v[138:139]
	v_cvt_f32_f16_sdwa v153, v115 dst_sel:DWORD dst_unused:UNUSED_PAD src0_sel:WORD_1
	v_cvt_f32_f16_e32 v152, v115
	v_pk_add_f32 v[154:155], v[146:147], v[148:149]
	v_and_or_b32 v2, v1, 64, v85
	v_pk_add_f32 v[156:157], v[154:155], v[150:151]
	v_lshlrev_b32_e32 v2, 2, v2
	v_pk_add_f32 v[158:159], v[156:157], v[116:117]
	v_exp_f32_e32 v134, v134
	v_pk_add_f32 v[160:161], v[158:159], v[152:153]
	ds_bpermute_b32 v94, v2, v160
	ds_bpermute_b32 v95, v2, v161
	ds_bpermute_b32 v162, v2, v160 offset:64
	ds_bpermute_b32 v163, v2, v161 offset:64
	ds_bpermute_b32 v164, v2, v160 offset:128
	ds_bpermute_b32 v165, v2, v161 offset:128
	ds_bpermute_b32 v166, v2, v160 offset:192
	ds_bpermute_b32 v167, v2, v161 offset:192
	s_waitcnt lgkmcnt(6)
	v_cndmask_b32_e64 v169, 0, v95, s[12:13]
	v_cndmask_b32_e64 v168, 0, v94, s[12:13]
	s_waitcnt lgkmcnt(4)
	v_cndmask_b32_e64 v171, 0, v163, s[10:11]
	v_cndmask_b32_e64 v170, 0, v162, s[10:11]
	v_pk_add_f32 v[168:169], v[168:169], v[170:171]
	s_waitcnt lgkmcnt(2)
	v_cndmask_b32_e64 v171, 0, v165, s[8:9]
	v_cndmask_b32_e64 v170, 0, v164, s[8:9]
	v_pk_add_f32 v[94:95], v[94:95], v[162:163]
	s_waitcnt lgkmcnt(0)
	v_pk_add_f32 v[162:163], v[164:165], v[166:167]
	v_pk_add_f32 v[168:169], v[168:169], v[170:171]
	v_pk_add_f32 v[94:95], v[94:95], v[162:163]
	v_exp_f32_e32 v135, v135
	v_pk_add_f32 v[162:163], v[94:95], v[168:169] neg_lo:[0,1] neg_hi:[0,1]
	ds_write_b128 v100, v[72:75] offset:30720
	ds_write_b128 v100, v[68:71] offset:30736
	v_pk_add_f32 v[162:163], v[86:87], v[162:163]
	v_pk_add_f32 v[68:69], v[134:135], 1.0 op_sel_hi:[1,0] neg_lo:[1,0] neg_hi:[1,0]
	v_pk_add_f32 v[140:141], v[162:163], v[140:141] neg_lo:[0,1] neg_hi:[0,1]
	v_exp_f32_e32 v70, v136
	v_exp_f32_e32 v140, v140
	v_exp_f32_e32 v141, v141
	v_exp_f32_e32 v71, v137
	v_mad_u64_u32 v[72:73], s[16:17], v96, s15, v[90:91]
	v_pk_mul_f32 v[68:69], v[68:69], v[140:141]
	v_pk_add_f32 v[70:71], v[70:71], 1.0 op_sel_hi:[1,0] neg_lo:[1,0] neg_hi:[1,0]
	v_cvt_pk_bf16_f32 v2, v68, v69
	v_pk_add_f32 v[68:69], v[162:163], v[142:143] neg_lo:[0,1] neg_hi:[0,1]
	v_add_u32_e32 v73, 0x5000, v72
	v_exp_f32_e32 v68, v68
	v_exp_f32_e32 v69, v69
	v_pk_add_f32 v[74:75], v[162:163], v[146:147] neg_lo:[0,1] neg_hi:[0,1]
	s_and_b64 s[16:17], s[4:5], exec
	v_exp_f32_e32 v74, v74
	v_pk_mul_f32 v[68:69], v[70:71], v[68:69]
	v_exp_f32_e32 v75, v75
	v_cvt_pk_bf16_f32 v70, v68, v69
	v_exp_f32_e32 v68, v122
	v_exp_f32_e32 v69, v123
	ds_write2_b32 v73, v2, v70 offset1:80
	v_pk_add_f32 v[70:71], v[162:163], v[144:145] neg_lo:[0,1] neg_hi:[0,1]
	v_exp_f32_e32 v122, v138
	v_exp_f32_e32 v70, v70
	v_exp_f32_e32 v71, v71
	v_exp_f32_e32 v123, v139
	v_pk_add_f32 v[68:69], v[68:69], 1.0 op_sel_hi:[1,0] neg_lo:[1,0] neg_hi:[1,0]
	s_cselect_b32 s2, 0, 0xe0
	v_pk_mul_f32 v[68:69], v[68:69], v[70:71]
	v_exp_f32_e32 v70, v148
	v_cvt_pk_bf16_f32 v2, v68, v69
	v_pk_add_f32 v[68:69], v[122:123], 1.0 op_sel_hi:[1,0] neg_lo:[1,0] neg_hi:[1,0]
	v_exp_f32_e32 v71, v149
	v_pk_mul_f32 v[68:69], v[68:69], v[74:75]
	v_pk_add_f32 v[74:75], v[162:163], v[156:157] neg_lo:[0,1] neg_hi:[0,1]
	v_cvt_pk_bf16_f32 v68, v68, v69
	ds_write2_b32 v73, v2, v68 offset0:160 offset1:240
	v_pk_add_f32 v[68:69], v[162:163], v[154:155] neg_lo:[0,1] neg_hi:[0,1]
	v_exp_f32_e32 v122, v150
	v_exp_f32_e32 v68, v68
	v_exp_f32_e32 v69, v69
	v_exp_f32_e32 v123, v151
	v_exp_f32_e32 v74, v74
	v_exp_f32_e32 v75, v75
	v_pk_add_f32 v[70:71], v[70:71], 1.0 op_sel_hi:[1,0] neg_lo:[1,0] neg_hi:[1,0]
	v_pk_add_f32 v[86:87], v[86:87], v[94:95]
	v_pk_mul_f32 v[68:69], v[70:71], v[68:69]
	v_add_u32_e32 v71, 0x5400, v72
	v_cvt_pk_bf16_f32 v2, v68, v69
	v_pk_add_f32 v[68:69], v[122:123], 1.0 op_sel_hi:[1,0] neg_lo:[1,0] neg_hi:[1,0]
	s_nop 0
	v_pk_mul_f32 v[68:69], v[68:69], v[74:75]
	v_pk_add_f32 v[74:75], v[162:163], v[160:161] neg_lo:[0,1] neg_hi:[0,1]
	v_cvt_pk_bf16_f32 v70, v68, v69
	v_exp_f32_e32 v68, v116
	v_exp_f32_e32 v69, v117
	ds_write2_b32 v71, v2, v70 offset0:64 offset1:144
	v_pk_add_f32 v[70:71], v[162:163], v[158:159] neg_lo:[0,1] neg_hi:[0,1]
	v_exp_f32_e32 v116, v152
	v_exp_f32_e32 v70, v70
	v_exp_f32_e32 v71, v71
	v_exp_f32_e32 v117, v153
	v_exp_f32_e32 v74, v74
	v_exp_f32_e32 v75, v75
	v_pk_add_f32 v[68:69], v[68:69], 1.0 op_sel_hi:[1,0] neg_lo:[1,0] neg_hi:[1,0]
	s_nop 0
	v_pk_mul_f32 v[68:69], v[68:69], v[70:71]
	s_nop 0
	v_cvt_pk_bf16_f32 v2, v68, v69
	v_pk_add_f32 v[68:69], v[116:117], 1.0 op_sel_hi:[1,0] neg_lo:[1,0] neg_hi:[1,0]
	s_nop 0
	v_pk_mul_f32 v[68:69], v[68:69], v[74:75]
	s_nop 0
	v_cvt_pk_bf16_f32 v68, v68, v69
	v_add_u32_e32 v69, 0x5600, v72
	ds_write2_b32 v69, v2, v68 offset0:96 offset1:176
	v_add_u32_e32 v68, s2, v101
	v_ashrrev_i32_e32 v69, 31, v68
	v_lshlrev_b64 v[68:69], 11, v[68:69]
	v_lshl_add_u64 v[68:69], s[20:21], 0, v[68:69]
	v_lshl_add_u64 v[68:69], s[38:39], 1, v[68:69]
	v_lshl_add_u64 v[72:73], v[88:89], 1, v[68:69]
	global_load_dwordx4 v[68:71], v[72:73], off offset:16
	s_nop 0
	global_load_dwordx4 v[72:75], v[72:73], off
	v_cndmask_b32_e64 v2, v120, v119, s[4:5]
	ds_read_b64_tr_b16 v[116:117], v97 offset:10240
	ds_read_b64_tr_b16 v[118:119], v97 offset:11520
	ds_read_b64_tr_b16 v[134:135], v97 offset:15360
	ds_read_b64_tr_b16 v[136:137], v97 offset:16640
	s_or_b32 s2, s66, s2
	v_add_u32_e32 v88, s2, v2
	v_add3_u32 v2, s65, v99, v98
	ds_read_b64_tr_b16 v[120:121], v2
	ds_read_b64_tr_b16 v[122:123], v2 offset:1280
	ds_read_b64_tr_b16 v[138:139], v2 offset:5120
	ds_read_b64_tr_b16 v[140:141], v2 offset:6400
	ds_read_b64_tr_b16 v[142:143], v2 offset:64
	ds_read_b64_tr_b16 v[146:147], v2 offset:128
	ds_read_b64_tr_b16 v[150:151], v2 offset:192
	ds_read_b64_tr_b16 v[144:145], v2 offset:1344
	ds_read_b64_tr_b16 v[148:149], v2 offset:1408
	ds_read_b64_tr_b16 v[152:153], v2 offset:1472
	s_waitcnt lgkmcnt(8)
	v_mfma_f32_32x32x16_bf16 v[52:67], v[120:123], v[116:119], v[52:67]
	ds_read_b64_tr_b16 v[120:121], v2 offset:5184
	ds_read_b64_tr_b16 v[154:155], v2 offset:5248
	ds_read_b64_tr_b16 v[158:159], v2 offset:5312
	ds_read_b64_tr_b16 v[122:123], v2 offset:6464
	ds_read_b64_tr_b16 v[156:157], v2 offset:6528
	ds_read_b64_tr_b16 v[160:161], v2 offset:6592
	v_cndmask_b32_e64 v2, v114, v112, s[4:5]
	v_add_u32_e32 v114, s2, v2
	v_cndmask_b32_e64 v2, v113, v110, s[4:5]
	v_ashrrev_i32_e32 v115, 31, v114
	v_add_u32_e32 v112, s2, v2
	v_cndmask_b32_e64 v2, v111, v107, s[4:5]
	s_waitcnt lgkmcnt(8)
	v_mfma_f32_32x32x16_bf16 v[36:51], v[142:145], v[116:119], v[36:51]
	v_lshlrev_b64 v[114:115], 11, v[114:115]
	v_add_u32_e32 v110, s2, v2
	v_cndmask_b32_e64 v2, v109, v105, s[4:5]
	v_ashrrev_i32_e32 v89, 31, v88
	v_add_u32_e32 v104, s2, v104
	v_lshlrev_b64 v[88:89], 11, v[88:89]
	v_ashrrev_i32_e32 v113, 31, v112
	v_mfma_f32_32x32x16_bf16 v[52:67], v[138:141], v[134:137], v[52:67]
	v_lshl_add_u64 v[138:139], v[92:93], 0, v[114:115]
	v_add_u32_e32 v114, s2, v2
	v_cndmask_b32_e64 v2, v108, v103, s[4:5]
	v_add_u32_e32 v108, s2, v2
	v_cndmask_b32_e64 v2, v106, v102, s[4:5]
	v_ashrrev_i32_e32 v115, 31, v114
	v_add_u32_e32 v102, s2, v2
	v_ashrrev_i32_e32 v111, 31, v110
	v_lshlrev_b64 v[114:115], 11, v[114:115]
	v_ashrrev_i32_e32 v109, 31, v108
	v_ashrrev_i32_e32 v103, 31, v102
	v_ashrrev_i32_e32 v105, 31, v104
	v_lshl_add_u64 v[88:89], v[92:93], 0, v[88:89]
	v_lshlrev_b64 v[112:113], 11, v[112:113]
	s_waitcnt lgkmcnt(2)
	v_mfma_f32_32x32x16_bf16 v[36:51], v[120:123], v[134:137], v[36:51]
	v_lshlrev_b64 v[110:111], 11, v[110:111]
	v_lshl_add_u64 v[120:121], v[92:93], 0, v[114:115]
	v_lshlrev_b64 v[108:109], 11, v[108:109]
	v_lshlrev_b64 v[102:103], 11, v[102:103]
	v_lshlrev_b64 v[104:105], 11, v[104:105]
	v_lshl_add_u64 v[112:113], v[92:93], 0, v[112:113]
	v_lshl_add_u64 v[110:111], v[92:93], 0, v[110:111]
	v_mfma_f32_32x32x16_bf16 v[20:35], v[146:149], v[116:119], v[20:35]
	v_lshl_add_u64 v[108:109], v[92:93], 0, v[108:109]
	v_lshl_add_u64 v[102:103], v[92:93], 0, v[102:103]
	v_lshl_add_u64 v[92:93], v[92:93], 0, v[104:105]
	v_mfma_f32_32x32x16_bf16 v[4:19], v[150:153], v[116:119], v[4:19]
	global_load_dword v115, v[88:89], off
	global_load_dword v116, v[138:139], off
	global_load_dword v117, v[112:113], off
	global_load_dword v118, v[110:111], off
	s_nop 0
	global_load_dword v121, v[120:121], off
	s_nop 0
	global_load_dword v122, v[108:109], off
	global_load_dword v123, v[102:103], off
	global_load_dword v124, v[92:93], off
	s_waitcnt lgkmcnt(1)
	v_mfma_f32_32x32x16_bf16 v[20:35], v[154:157], v[134:137], v[20:35]
	s_waitcnt lgkmcnt(0)
	v_mfma_f32_32x32x16_bf16 v[4:19], v[158:161], v[134:137], v[4:19]
.LBB0_1166:
	s_and_b64 vcc, exec, s[6:7]
	s_barrier
	s_cbranch_vccnz .LBB0_1168
	s_waitcnt vmcnt(10)
	v_cvt_f32_f16_sdwa v89, v132 dst_sel:DWORD dst_unused:UNUSED_PAD src0_sel:WORD_1
	v_cvt_f32_f16_e32 v88, v132
	s_waitcnt vmcnt(10)
	v_cvt_f32_f16_sdwa v93, v131 dst_sel:DWORD dst_unused:UNUSED_PAD src0_sel:WORD_1
	v_cvt_f32_f16_e32 v92, v131
	s_waitcnt vmcnt(10)
	v_cvt_f32_f16_sdwa v95, v130 dst_sel:DWORD dst_unused:UNUSED_PAD src0_sel:WORD_1
	v_cvt_f32_f16_e32 v94, v130
	s_waitcnt vmcnt(10)
	v_cvt_f32_f16_sdwa v103, v129 dst_sel:DWORD dst_unused:UNUSED_PAD src0_sel:WORD_1
	v_cvt_f32_f16_e32 v102, v129
	v_pk_add_f32 v[104:105], v[88:89], 0 op_sel_hi:[1,0]
	s_waitcnt vmcnt(10)
	v_cvt_f32_f16_sdwa v113, v128 dst_sel:DWORD dst_unused:UNUSED_PAD src0_sel:WORD_1
	v_cvt_f32_f16_e32 v112, v128
	v_pk_add_f32 v[106:107], v[104:105], v[92:93]
	s_waitcnt vmcnt(10)
	v_cvt_f32_f16_sdwa v129, v127 dst_sel:DWORD dst_unused:UNUSED_PAD src0_sel:WORD_1
	v_cvt_f32_f16_e32 v128, v127
	v_pk_add_f32 v[108:109], v[106:107], v[94:95]
	s_waitcnt vmcnt(10)
	v_cvt_f32_f16_sdwa v127, v126 dst_sel:DWORD dst_unused:UNUSED_PAD src0_sel:WORD_1
	v_cvt_f32_f16_e32 v126, v126
	v_pk_add_f32 v[110:111], v[108:109], v[102:103]
	s_waitcnt vmcnt(10)
	v_cvt_f32_f16_sdwa v131, v125 dst_sel:DWORD dst_unused:UNUSED_PAD src0_sel:WORD_1
	v_cvt_f32_f16_e32 v130, v125
	v_pk_add_f32 v[132:133], v[110:111], v[112:113]
	v_and_or_b32 v2, v1, 64, v85
	v_pk_add_f32 v[134:135], v[132:133], v[128:129]
	v_lshlrev_b32_e32 v2, 2, v2
	v_pk_add_f32 v[136:137], v[134:135], v[126:127]
	v_exp_f32_e32 v88, v88
	v_pk_add_f32 v[138:139], v[136:137], v[130:131]
	ds_bpermute_b32 v140, v2, v138
	ds_bpermute_b32 v141, v2, v139
	ds_bpermute_b32 v142, v2, v138 offset:64
	ds_bpermute_b32 v143, v2, v139 offset:64
	ds_bpermute_b32 v144, v2, v138 offset:128
	ds_bpermute_b32 v145, v2, v139 offset:128
	ds_bpermute_b32 v146, v2, v138 offset:192
	ds_bpermute_b32 v147, v2, v139 offset:192
	s_waitcnt lgkmcnt(6)
	v_cndmask_b32_e64 v149, 0, v141, s[12:13]
	v_cndmask_b32_e64 v148, 0, v140, s[12:13]
	s_waitcnt lgkmcnt(4)
	v_cndmask_b32_e64 v151, 0, v143, s[10:11]
	v_cndmask_b32_e64 v150, 0, v142, s[10:11]
	v_pk_add_f32 v[148:149], v[148:149], v[150:151]
	s_waitcnt lgkmcnt(2)
	v_cndmask_b32_e64 v151, 0, v145, s[8:9]
	v_cndmask_b32_e64 v150, 0, v144, s[8:9]
	v_pk_add_f32 v[140:141], v[140:141], v[142:143]
	s_waitcnt lgkmcnt(0)
	v_pk_add_f32 v[142:143], v[144:145], v[146:147]
	v_pk_add_f32 v[148:149], v[148:149], v[150:151]
	v_pk_add_f32 v[140:141], v[140:141], v[142:143]
	v_exp_f32_e32 v89, v89
	v_pk_add_f32 v[142:143], v[140:141], v[148:149] neg_lo:[0,1] neg_hi:[0,1]
	s_waitcnt vmcnt(10)
	ds_write_b128 v100, v[80:83] offset:10240
	ds_write_b128 v100, v[76:79] offset:10256
	v_pk_add_f32 v[142:143], v[86:87], v[142:143]
	v_pk_add_f32 v[76:77], v[88:89], 1.0 op_sel_hi:[1,0] neg_lo:[1,0] neg_hi:[1,0]
	v_pk_add_f32 v[104:105], v[142:143], v[104:105] neg_lo:[0,1] neg_hi:[0,1]
	v_exp_f32_e32 v78, v92
	v_exp_f32_e32 v104, v104
	v_exp_f32_e32 v105, v105
	v_exp_f32_e32 v79, v93
	v_mad_u64_u32 v[80:81], s[16:17], v96, s15, v[90:91]
	v_pk_mul_f32 v[76:77], v[76:77], v[104:105]
	v_pk_add_f32 v[78:79], v[78:79], 1.0 op_sel_hi:[1,0] neg_lo:[1,0] neg_hi:[1,0]
	v_cvt_pk_bf16_f32 v2, v76, v77
	v_pk_add_f32 v[76:77], v[142:143], v[106:107] neg_lo:[0,1] neg_hi:[0,1]
	v_pk_add_f32 v[82:83], v[142:143], v[110:111] neg_lo:[0,1] neg_hi:[0,1]
	v_exp_f32_e32 v76, v76
	v_exp_f32_e32 v77, v77
	v_exp_f32_e32 v88, v102
	v_exp_f32_e32 v89, v103
	v_exp_f32_e32 v82, v82
	v_pk_mul_f32 v[76:77], v[78:79], v[76:77]
	v_exp_f32_e32 v78, v94
	v_cvt_pk_bf16_f32 v76, v76, v77
	v_exp_f32_e32 v79, v95
	ds_write2_b32 v80, v2, v76 offset1:80
	v_pk_add_f32 v[76:77], v[142:143], v[108:109] neg_lo:[0,1] neg_hi:[0,1]
	v_exp_f32_e32 v83, v83
	v_exp_f32_e32 v76, v76
	v_exp_f32_e32 v77, v77
	v_pk_add_f32 v[78:79], v[78:79], 1.0 op_sel_hi:[1,0] neg_lo:[1,0] neg_hi:[1,0]
	v_pk_add_f32 v[86:87], v[86:87], v[140:141]
	v_pk_mul_f32 v[76:77], v[78:79], v[76:77]
	s_nop 0
	v_cvt_pk_bf16_f32 v2, v76, v77
	v_pk_add_f32 v[76:77], v[88:89], 1.0 op_sel_hi:[1,0] neg_lo:[1,0] neg_hi:[1,0]
	v_exp_f32_e32 v78, v112
	v_pk_mul_f32 v[76:77], v[76:77], v[82:83]
	v_exp_f32_e32 v79, v113
	v_cvt_pk_bf16_f32 v76, v76, v77
	ds_write2_b32 v80, v2, v76 offset0:160 offset1:240
	v_pk_add_f32 v[76:77], v[142:143], v[132:133] neg_lo:[0,1] neg_hi:[0,1]
	v_pk_add_f32 v[82:83], v[142:143], v[134:135] neg_lo:[0,1] neg_hi:[0,1]
	v_exp_f32_e32 v76, v76
	v_exp_f32_e32 v77, v77
	v_exp_f32_e32 v88, v128
	v_exp_f32_e32 v89, v129
	v_exp_f32_e32 v82, v82
	v_exp_f32_e32 v83, v83
	v_pk_add_f32 v[78:79], v[78:79], 1.0 op_sel_hi:[1,0] neg_lo:[1,0] neg_hi:[1,0]
	s_nop 0
	v_pk_mul_f32 v[76:77], v[78:79], v[76:77]
	v_add_u32_e32 v79, 0x400, v80
	v_cvt_pk_bf16_f32 v2, v76, v77
	v_pk_add_f32 v[76:77], v[88:89], 1.0 op_sel_hi:[1,0] neg_lo:[1,0] neg_hi:[1,0]
	v_exp_f32_e32 v88, v130
	v_pk_mul_f32 v[76:77], v[76:77], v[82:83]
	v_pk_add_f32 v[82:83], v[142:143], v[138:139] neg_lo:[0,1] neg_hi:[0,1]
	v_cvt_pk_bf16_f32 v78, v76, v77
	v_exp_f32_e32 v76, v126
	v_exp_f32_e32 v77, v127
	ds_write2_b32 v79, v2, v78 offset0:64 offset1:144
	v_pk_add_f32 v[78:79], v[142:143], v[136:137] neg_lo:[0,1] neg_hi:[0,1]
	v_exp_f32_e32 v89, v131
	v_exp_f32_e32 v78, v78
	v_exp_f32_e32 v79, v79
	v_exp_f32_e32 v82, v82
	v_exp_f32_e32 v83, v83
	v_pk_add_f32 v[76:77], v[76:77], 1.0 op_sel_hi:[1,0] neg_lo:[1,0] neg_hi:[1,0]
	s_nop 0
	v_pk_mul_f32 v[76:77], v[76:77], v[78:79]
	s_nop 0
	v_cvt_pk_bf16_f32 v2, v76, v77
	v_pk_add_f32 v[76:77], v[88:89], 1.0 op_sel_hi:[1,0] neg_lo:[1,0] neg_hi:[1,0]
	s_nop 0
	v_pk_mul_f32 v[76:77], v[76:77], v[82:83]
	s_nop 0
	v_cvt_pk_bf16_f32 v76, v76, v77
	v_add_u32_e32 v77, 0x600, v80
	ds_write2_b32 v77, v2, v76 offset0:96 offset1:176
	v_add3_u32 v2, s65, v99, v98
	ds_read_b64_tr_b16 v[76:77], v97 offset:30720
	ds_read_b64_tr_b16 v[78:79], v97 offset:32000
	ds_read_b64_tr_b16 v[82:83], v97 offset:37120
	ds_read_b64_tr_b16 v[92:93], v2 offset:20480
	ds_read_b64_tr_b16 v[94:95], v2 offset:21760
	ds_read_b64_tr_b16 v[102:103], v2 offset:25600
	ds_read_b64_tr_b16 v[104:105], v2 offset:26880
	ds_read_b64_tr_b16 v[106:107], v2 offset:20544
	ds_read_b64_tr_b16 v[110:111], v2 offset:20608
	ds_read_b64_tr_b16 v[126:127], v2 offset:20672
	ds_read_b64_tr_b16 v[108:109], v2 offset:21824
	ds_read_b64_tr_b16 v[112:113], v2 offset:21888
	ds_read_b64_tr_b16 v[128:129], v2 offset:21952
	s_waitcnt lgkmcnt(8)
	v_mfma_f32_32x32x16_bf16 v[52:67], v[92:95], v[76:79], v[52:67]
	ds_read_b64_tr_b16 v[80:81], v97 offset:35840
	ds_read_b64_tr_b16 v[92:93], v2 offset:25664
	ds_read_b64_tr_b16 v[130:131], v2 offset:25728
	ds_read_b64_tr_b16 v[134:135], v2 offset:25792
	ds_read_b64_tr_b16 v[94:95], v2 offset:26944
	ds_read_b64_tr_b16 v[132:133], v2 offset:27008
	ds_read_b64_tr_b16 v[136:137], v2 offset:27072
	s_waitcnt lgkmcnt(9)
	v_mfma_f32_32x32x16_bf16 v[36:51], v[106:109], v[76:79], v[36:51]
	s_waitcnt lgkmcnt(8)
	v_mfma_f32_32x32x16_bf16 v[20:35], v[110:113], v[76:79], v[20:35]
	s_waitcnt lgkmcnt(7)
	v_mfma_f32_32x32x16_bf16 v[4:19], v[126:129], v[76:79], v[4:19]
	s_waitcnt lgkmcnt(6)
	v_mfma_f32_32x32x16_bf16 v[52:67], v[102:105], v[80:83], v[52:67]
	s_waitcnt lgkmcnt(2)
	v_mfma_f32_32x32x16_bf16 v[36:51], v[92:95], v[80:83], v[36:51]
	s_waitcnt lgkmcnt(1)
	v_mfma_f32_32x32x16_bf16 v[20:35], v[130:133], v[80:83], v[20:35]
	s_waitcnt lgkmcnt(0)
	v_mfma_f32_32x32x16_bf16 v[4:19], v[134:137], v[80:83], v[4:19]

.LBB0_1197:
	s_and_b64 vcc, exec, s[6:7]
	s_barrier
	s_cbranch_vccnz .LBB0_1199
	s_waitcnt vmcnt(10)
	v_cvt_f32_f16_sdwa v123, v122 dst_sel:DWORD dst_unused:UNUSED_PAD src0_sel:WORD_1
	v_cvt_f32_f16_e32 v122, v122
	s_waitcnt vmcnt(10)
	v_cvt_f32_f16_sdwa v125, v121 dst_sel:DWORD dst_unused:UNUSED_PAD src0_sel:WORD_1
	v_cvt_f32_f16_e32 v124, v121
	s_waitcnt vmcnt(10)
	v_cvt_f32_f16_sdwa v121, v120 dst_sel:DWORD dst_unused:UNUSED_PAD src0_sel:WORD_1
	v_cvt_f32_f16_e32 v120, v120
	s_waitcnt vmcnt(10)
	v_cvt_f32_f16_sdwa v127, v119 dst_sel:DWORD dst_unused:UNUSED_PAD src0_sel:WORD_1
	v_cvt_f32_f16_e32 v126, v119
	v_pk_add_f32 v[128:129], v[122:123], 0 op_sel_hi:[1,0]
	s_waitcnt vmcnt(10)
	v_cvt_f32_f16_sdwa v119, v118 dst_sel:DWORD dst_unused:UNUSED_PAD src0_sel:WORD_1
	v_cvt_f32_f16_e32 v118, v118
	v_pk_add_f32 v[130:131], v[128:129], v[124:125]
	s_waitcnt vmcnt(10)
	v_cvt_f32_f16_sdwa v137, v117 dst_sel:DWORD dst_unused:UNUSED_PAD src0_sel:WORD_1
	v_cvt_f32_f16_e32 v136, v117
	v_pk_add_f32 v[132:133], v[130:131], v[120:121]
	s_waitcnt vmcnt(10)
	v_cvt_f32_f16_sdwa v117, v116 dst_sel:DWORD dst_unused:UNUSED_PAD src0_sel:WORD_1
	v_cvt_f32_f16_e32 v116, v116
	v_pk_add_f32 v[134:135], v[132:133], v[126:127]
	s_waitcnt vmcnt(10)
	v_cvt_f32_f16_sdwa v139, v115 dst_sel:DWORD dst_unused:UNUSED_PAD src0_sel:WORD_1
	v_cvt_f32_f16_e32 v138, v115
	v_pk_add_f32 v[140:141], v[134:135], v[118:119]
	v_lshlrev_b32_e32 v115, 2, v89
	v_pk_add_f32 v[142:143], v[140:141], v[136:137]
	v_exp_f32_e32 v122, v122
	v_pk_add_f32 v[144:145], v[142:143], v[116:117]
	v_exp_f32_e32 v123, v123
	v_pk_add_f32 v[146:147], v[144:145], v[138:139]
	ds_bpermute_b32 v92, v115, v146
	ds_bpermute_b32 v93, v115, v147
	ds_bpermute_b32 v148, v115, v146 offset:64
	ds_bpermute_b32 v149, v115, v147 offset:64
	ds_bpermute_b32 v150, v115, v146 offset:128
	ds_bpermute_b32 v151, v115, v147 offset:128
	ds_bpermute_b32 v152, v115, v146 offset:192
	ds_bpermute_b32 v153, v115, v147 offset:192
	s_waitcnt lgkmcnt(6)
	v_cndmask_b32_e64 v155, 0, v93, s[12:13]
	v_cndmask_b32_e64 v154, 0, v92, s[12:13]
	s_waitcnt lgkmcnt(4)
	v_cndmask_b32_e64 v157, 0, v149, s[10:11]
	v_cndmask_b32_e64 v156, 0, v148, s[10:11]
	v_pk_add_f32 v[154:155], v[154:155], v[156:157]
	s_waitcnt lgkmcnt(2)
	v_cndmask_b32_e64 v157, 0, v151, s[8:9]
	v_cndmask_b32_e64 v156, 0, v150, s[8:9]
	v_pk_add_f32 v[92:93], v[92:93], v[148:149]
	s_waitcnt lgkmcnt(0)
	v_pk_add_f32 v[148:149], v[150:151], v[152:153]
	v_pk_add_f32 v[154:155], v[154:155], v[156:157]
	v_pk_add_f32 v[92:93], v[92:93], v[148:149]
	s_waitcnt vmcnt(10)
	ds_write_b128 v97, v[78:81] offset:10240
	ds_write_b128 v97, v[74:77] offset:10256
	v_pk_add_f32 v[148:149], v[92:93], v[154:155] neg_lo:[0,1] neg_hi:[0,1]
	v_pk_add_f32 v[74:75], v[122:123], 1.0 op_sel_hi:[1,0] neg_lo:[1,0] neg_hi:[1,0]
	v_pk_add_f32 v[148:149], v[84:85], v[148:149]
	v_exp_f32_e32 v76, v124
	v_pk_add_f32 v[128:129], v[148:149], v[128:129] neg_lo:[0,1] neg_hi:[0,1]
	v_exp_f32_e32 v77, v125
	v_exp_f32_e32 v128, v128
	v_exp_f32_e32 v129, v129
	s_movk_i32 s16, 0x140
	v_pk_add_f32 v[76:77], v[76:77], 1.0 op_sel_hi:[1,0] neg_lo:[1,0] neg_hi:[1,0]
	v_mad_u64_u32 v[78:79], s[18:19], v83, s16, v[88:89]
	v_pk_mul_f32 v[74:75], v[74:75], v[128:129]
	s_movk_i32 s2, 0x60
	v_cvt_pk_bf16_f32 v80, v74, v75
	v_pk_add_f32 v[74:75], v[148:149], v[130:131] neg_lo:[0,1] neg_hi:[0,1]
	s_and_b64 s[18:19], s[4:5], exec
	v_exp_f32_e32 v74, v74
	v_exp_f32_e32 v75, v75
	s_cselect_b32 s2, s2, 0x80
	s_or_b32 s17, s2, s47
	v_sub_u32_e32 v115, 31, v102
	v_pk_mul_f32 v[74:75], v[76:77], v[74:75]
	v_exp_f32_e32 v76, v120
	v_cvt_pk_bf16_f32 v74, v74, v75
	v_exp_f32_e32 v77, v121
	ds_write2_b32 v78, v80, v74 offset1:80
	v_pk_add_f32 v[74:75], v[148:149], v[132:133] neg_lo:[0,1] neg_hi:[0,1]
	v_pk_add_f32 v[80:81], v[148:149], v[134:135] neg_lo:[0,1] neg_hi:[0,1]
	v_exp_f32_e32 v74, v74
	v_exp_f32_e32 v75, v75
	v_exp_f32_e32 v120, v126
	v_exp_f32_e32 v121, v127
	v_exp_f32_e32 v80, v80
	v_exp_f32_e32 v81, v81
	v_pk_add_f32 v[76:77], v[76:77], 1.0 op_sel_hi:[1,0] neg_lo:[1,0] neg_hi:[1,0]
	v_cndmask_b32_e64 v115, v115, v102, s[4:5]
	v_pk_mul_f32 v[74:75], v[76:77], v[74:75]
	v_exp_f32_e32 v76, v118
	v_cvt_pk_bf16_f32 v79, v74, v75
	v_pk_add_f32 v[74:75], v[120:121], 1.0 op_sel_hi:[1,0] neg_lo:[1,0] neg_hi:[1,0]
	v_exp_f32_e32 v77, v119
	v_pk_mul_f32 v[74:75], v[74:75], v[80:81]
	v_pk_add_f32 v[80:81], v[148:149], v[142:143] neg_lo:[0,1] neg_hi:[0,1]
	v_cvt_pk_bf16_f32 v74, v74, v75
	ds_write2_b32 v78, v79, v74 offset0:160 offset1:240
	v_pk_add_f32 v[74:75], v[148:149], v[140:141] neg_lo:[0,1] neg_hi:[0,1]
	v_exp_f32_e32 v118, v136
	v_exp_f32_e32 v74, v74
	v_exp_f32_e32 v75, v75
	v_exp_f32_e32 v119, v137
	v_exp_f32_e32 v80, v80
	v_exp_f32_e32 v81, v81
	v_pk_add_f32 v[76:77], v[76:77], 1.0 op_sel_hi:[1,0] neg_lo:[1,0] neg_hi:[1,0]
	v_add_u32_e32 v79, 0x400, v78
	v_pk_mul_f32 v[74:75], v[76:77], v[74:75]
	v_pk_add_f32 v[84:85], v[84:85], v[92:93]
	v_cvt_pk_bf16_f32 v76, v74, v75
	v_pk_add_f32 v[74:75], v[118:119], 1.0 op_sel_hi:[1,0] neg_lo:[1,0] neg_hi:[1,0]
	s_nop 0
	v_pk_mul_f32 v[74:75], v[74:75], v[80:81]
	v_pk_add_f32 v[80:81], v[148:149], v[146:147] neg_lo:[0,1] neg_hi:[0,1]
	v_cvt_pk_bf16_f32 v77, v74, v75
	v_exp_f32_e32 v74, v116
	v_exp_f32_e32 v75, v117
	ds_write2_b32 v79, v76, v77 offset0:64 offset1:144
	v_pk_add_f32 v[76:77], v[148:149], v[144:145] neg_lo:[0,1] neg_hi:[0,1]
	v_exp_f32_e32 v116, v138
	v_exp_f32_e32 v76, v76
	v_exp_f32_e32 v77, v77
	v_exp_f32_e32 v117, v139
	v_exp_f32_e32 v80, v80
	v_exp_f32_e32 v81, v81
	v_pk_add_f32 v[74:75], v[74:75], 1.0 op_sel_hi:[1,0] neg_lo:[1,0] neg_hi:[1,0]
	s_nop 0
	v_pk_mul_f32 v[74:75], v[74:75], v[76:77]
	s_nop 0
	v_cvt_pk_bf16_f32 v76, v74, v75
	v_pk_add_f32 v[74:75], v[116:117], 1.0 op_sel_hi:[1,0] neg_lo:[1,0] neg_hi:[1,0]
	s_nop 0
	v_pk_mul_f32 v[74:75], v[74:75], v[80:81]
	s_nop 0
	v_cvt_pk_bf16_f32 v74, v74, v75
	v_add_u32_e32 v75, 0x600, v78
	ds_write2_b32 v75, v76, v74 offset0:96 offset1:176
	v_cndmask_b32_e64 v74, v100, v83, s[4:5]
	v_add_u32_e32 v74, s17, v74
	v_ashrrev_i32_e32 v75, 31, v74
	v_lshlrev_b64 v[74:75], 11, v[74:75]
	v_lshl_add_u64 v[144:145], v[90:91], 0, v[74:75]
	v_sub_u32_e32 v74, 31, v99
	v_cndmask_b32_e64 v74, v74, v99, s[4:5]
	v_add_u32_e32 v74, s17, v74
	v_ashrrev_i32_e32 v75, 31, v74
	v_lshlrev_b64 v[74:75], 11, v[74:75]
	v_lshl_add_u64 v[146:147], v[90:91], 0, v[74:75]
	v_sub_u32_e32 v74, 31, v101
	v_cndmask_b32_e64 v74, v74, v101, s[4:5]
	v_add_u32_e32 v74, s17, v74
	v_ashrrev_i32_e32 v75, 31, v74
	v_mul_lo_u32 v78, v94, s16
	v_lshlrev_b64 v[74:75], 11, v[74:75]
	v_add_u32_e32 v79, v95, v78
	v_lshl_add_u64 v[148:149], v[90:91], 0, v[74:75]
	ds_read_b64_tr_b16 v[74:75], v79 offset:30720
	ds_read_b64_tr_b16 v[76:77], v79 offset:32000
	ds_read_b64_tr_b16 v[124:125], v79 offset:35840
	ds_read_b64_tr_b16 v[126:127], v79 offset:37120
	v_add3_u32 v142, s46, v96, v78
	ds_read_b64_tr_b16 v[78:79], v142 offset:20480
	ds_read_b64_tr_b16 v[80:81], v142 offset:21760
	ds_read_b64_tr_b16 v[116:117], v142 offset:25600
	ds_read_b64_tr_b16 v[118:119], v142 offset:26880
	ds_read_b64_tr_b16 v[120:121], v142 offset:20544
	ds_read_b64_tr_b16 v[128:129], v142 offset:20608
	ds_read_b64_tr_b16 v[132:133], v142 offset:20672
	ds_read_b64_tr_b16 v[122:123], v142 offset:21824
	ds_read_b64_tr_b16 v[130:131], v142 offset:21888
	ds_read_b64_tr_b16 v[134:135], v142 offset:21952
	s_waitcnt lgkmcnt(8)
	v_mfma_f32_32x32x16_bf16 v[2:17], v[78:81], v[74:77], v[2:17]
	ds_read_b64_tr_b16 v[78:79], v142 offset:25664
	ds_read_b64_tr_b16 v[136:137], v142 offset:25728
	ds_read_b64_tr_b16 v[140:141], v142 offset:25792
	ds_read_b64_tr_b16 v[80:81], v142 offset:26944
	ds_read_b64_tr_b16 v[138:139], v142 offset:27008
	ds_read_b64_tr_b16 v[142:143], v142 offset:27072
	s_waitcnt lgkmcnt(8)
	v_mfma_f32_32x32x16_bf16 v[50:65], v[120:123], v[74:77], v[50:65]
	v_mfma_f32_32x32x16_bf16 v[2:17], v[116:119], v[124:127], v[2:17]
	v_add_u32_e32 v116, s17, v115
	v_sub_u32_e32 v115, 31, v103
	v_cndmask_b32_e64 v115, v115, v103, s[4:5]
	v_add_u32_e32 v118, s17, v115
	v_ashrrev_i32_e32 v119, 31, v118
	v_sub_u32_e32 v115, 31, v104
	v_lshlrev_b64 v[118:119], 11, v[118:119]
	v_cndmask_b32_e64 v115, v115, v104, s[4:5]
	v_lshl_add_u64 v[150:151], v[90:91], 0, v[118:119]
	v_add_u32_e32 v118, s17, v115
	s_waitcnt lgkmcnt(2)
	v_mfma_f32_32x32x16_bf16 v[50:65], v[78:81], v[124:127], v[50:65]
	v_sub_u32_e32 v80, 31, v108
	v_sub_u32_e32 v115, 31, v109
	v_ashrrev_i32_e32 v119, 31, v118
	v_cndmask_b32_e64 v80, v80, v108, s[4:5]
	v_cndmask_b32_e64 v115, v115, v109, s[4:5]
	v_ashrrev_i32_e32 v117, 31, v116
	v_lshlrev_b64 v[78:79], 11, v[118:119]
	v_add_u32_e32 v80, s17, v80
	v_add_u32_e32 v118, s17, v115
	v_lshlrev_b64 v[116:117], 11, v[116:117]
	v_ashrrev_i32_e32 v81, 31, v80
	v_ashrrev_i32_e32 v119, 31, v118
	v_lshl_add_u64 v[116:117], v[90:91], 0, v[116:117]
	v_lshl_add_u64 v[78:79], v[90:91], 0, v[78:79]
	v_lshlrev_b64 v[80:81], 11, v[80:81]
	v_lshlrev_b64 v[118:119], 11, v[118:119]
	v_mfma_f32_32x32x16_bf16 v[34:49], v[128:131], v[74:77], v[34:49]
	v_lshl_add_u64 v[80:81], v[90:91], 0, v[80:81]
	v_lshl_add_u64 v[128:129], v[90:91], 0, v[118:119]
	global_load_dword v122, v[144:145], off
	global_load_dword v121, v[146:147], off
	global_load_dword v120, v[148:149], off
	global_load_dword v119, v[116:117], off
	global_load_dword v118, v[150:151], off
	s_nop 0
	global_load_dword v117, v[78:79], off
	global_load_dword v116, v[80:81], off
	global_load_dword v115, v[128:129], off
	v_add_u32_e32 v78, s2, v98
	v_ashrrev_i32_e32 v79, 31, v78
	v_lshlrev_b64 v[78:79], 11, v[78:79]
	v_lshl_add_u64 v[78:79], s[20:21], 0, v[78:79]
	v_lshl_add_u64 v[78:79], s[38:39], 1, v[78:79]
	v_lshl_add_u64 v[78:79], v[86:87], 1, v[78:79]
	v_mfma_f32_32x32x16_bf16 v[18:33], v[132:135], v[74:77], v[18:33]
	global_load_dwordx4 v[74:77], v[78:79], off offset:16
	s_nop 0
	global_load_dwordx4 v[78:81], v[78:79], off
	s_waitcnt lgkmcnt(1)
	v_mfma_f32_32x32x16_bf16 v[34:49], v[136:139], v[124:127], v[34:49]
	s_waitcnt lgkmcnt(0)
	v_mfma_f32_32x32x16_bf16 v[18:33], v[140:143], v[124:127], v[18:33]
.LBB0_1199:
	s_and_b64 vcc, exec, s[6:7]
	s_barrier
	s_cbranch_vccnz .LBB0_1201
	s_waitcnt vmcnt(10)
	v_cvt_f32_f16_sdwa v125, v114 dst_sel:DWORD dst_unused:UNUSED_PAD src0_sel:WORD_1
	v_cvt_f32_f16_e32 v124, v114
	v_cvt_f32_f16_sdwa v127, v113 dst_sel:DWORD dst_unused:UNUSED_PAD src0_sel:WORD_1
	v_cvt_f32_f16_e32 v126, v113
	v_cvt_f32_f16_sdwa v113, v112 dst_sel:DWORD dst_unused:UNUSED_PAD src0_sel:WORD_1
	v_cvt_f32_f16_e32 v112, v112
	v_cvt_f32_f16_sdwa v129, v111 dst_sel:DWORD dst_unused:UNUSED_PAD src0_sel:WORD_1
	v_cvt_f32_f16_e32 v128, v111
	v_pk_add_f32 v[130:131], v[124:125], 0 op_sel_hi:[1,0]
	v_cvt_f32_f16_sdwa v111, v110 dst_sel:DWORD dst_unused:UNUSED_PAD src0_sel:WORD_1
	v_cvt_f32_f16_e32 v110, v110
	v_pk_add_f32 v[132:133], v[130:131], v[126:127]
	v_cvt_f32_f16_sdwa v139, v107 dst_sel:DWORD dst_unused:UNUSED_PAD src0_sel:WORD_1
	v_cvt_f32_f16_e32 v138, v107
	v_pk_add_f32 v[134:135], v[132:133], v[112:113]
	v_cvt_f32_f16_sdwa v107, v106 dst_sel:DWORD dst_unused:UNUSED_PAD src0_sel:WORD_1
	v_cvt_f32_f16_e32 v106, v106
	v_pk_add_f32 v[136:137], v[134:135], v[128:129]
	v_cvt_f32_f16_sdwa v141, v105 dst_sel:DWORD dst_unused:UNUSED_PAD src0_sel:WORD_1
	v_cvt_f32_f16_e32 v140, v105
	v_pk_add_f32 v[142:143], v[136:137], v[110:111]
	v_lshlrev_b32_e32 v105, 2, v89
	v_pk_add_f32 v[144:145], v[142:143], v[138:139]
	v_exp_f32_e32 v124, v124
	v_pk_add_f32 v[146:147], v[144:145], v[106:107]
	v_exp_f32_e32 v125, v125
	v_pk_add_f32 v[148:149], v[146:147], v[140:141]
	ds_bpermute_b32 v92, v105, v148
	ds_bpermute_b32 v93, v105, v149
	ds_bpermute_b32 v150, v105, v148 offset:64
	ds_bpermute_b32 v151, v105, v149 offset:64
	ds_bpermute_b32 v152, v105, v148 offset:128
	ds_bpermute_b32 v153, v105, v149 offset:128
	ds_bpermute_b32 v154, v105, v148 offset:192
	ds_bpermute_b32 v155, v105, v149 offset:192
	s_waitcnt lgkmcnt(6)
	v_cndmask_b32_e64 v157, 0, v93, s[12:13]
	v_cndmask_b32_e64 v156, 0, v92, s[12:13]
	s_waitcnt lgkmcnt(4)
	v_cndmask_b32_e64 v159, 0, v151, s[10:11]
	v_cndmask_b32_e64 v158, 0, v150, s[10:11]
	v_pk_add_f32 v[156:157], v[156:157], v[158:159]
	s_waitcnt lgkmcnt(2)
	v_cndmask_b32_e64 v159, 0, v153, s[8:9]
	v_cndmask_b32_e64 v158, 0, v152, s[8:9]
	v_pk_add_f32 v[92:93], v[92:93], v[150:151]
	s_waitcnt lgkmcnt(0)
	v_pk_add_f32 v[150:151], v[152:153], v[154:155]
	v_pk_add_f32 v[156:157], v[156:157], v[158:159]
	v_pk_add_f32 v[92:93], v[92:93], v[150:151]
	ds_write_b128 v97, v[70:73] offset:30720
	ds_write_b128 v97, v[66:69] offset:30736
	v_pk_add_f32 v[150:151], v[92:93], v[156:157] neg_lo:[0,1] neg_hi:[0,1]
	v_pk_add_f32 v[66:67], v[124:125], 1.0 op_sel_hi:[1,0] neg_lo:[1,0] neg_hi:[1,0]
	v_pk_add_f32 v[150:151], v[84:85], v[150:151]
	v_exp_f32_e32 v68, v126
	v_pk_add_f32 v[130:131], v[150:151], v[130:131] neg_lo:[0,1] neg_hi:[0,1]
	v_exp_f32_e32 v69, v127
	v_exp_f32_e32 v130, v130
	v_exp_f32_e32 v131, v131
	s_movk_i32 s2, 0x140
	v_pk_add_f32 v[68:69], v[68:69], 1.0 op_sel_hi:[1,0] neg_lo:[1,0] neg_hi:[1,0]
	v_mad_u64_u32 v[70:71], s[16:17], v83, s2, v[88:89]
	v_pk_mul_f32 v[66:67], v[66:67], v[130:131]
	v_add_u32_e32 v71, 0x5000, v70
	v_cvt_pk_bf16_f32 v72, v66, v67
	v_pk_add_f32 v[66:67], v[150:151], v[132:133] neg_lo:[0,1] neg_hi:[0,1]
	s_and_b64 s[16:17], s[4:5], exec
	v_exp_f32_e32 v66, v66
	v_exp_f32_e32 v67, v67
	s_cselect_b32 s16, 64, 0xa0
	v_pk_add_f32 v[84:85], v[84:85], v[92:93]
	v_pk_mul_f32 v[66:67], v[68:69], v[66:67]
	s_nop 0
	v_cvt_pk_bf16_f32 v68, v66, v67
	v_exp_f32_e32 v66, v112
	v_exp_f32_e32 v67, v113
	ds_write2_b32 v71, v72, v68 offset1:80
	v_pk_add_f32 v[68:69], v[150:151], v[134:135] neg_lo:[0,1] neg_hi:[0,1]
	v_pk_add_f32 v[72:73], v[150:151], v[136:137] neg_lo:[0,1] neg_hi:[0,1]
	v_exp_f32_e32 v68, v68
	v_exp_f32_e32 v69, v69
	v_exp_f32_e32 v112, v128
	v_exp_f32_e32 v113, v129
	v_exp_f32_e32 v72, v72
	v_exp_f32_e32 v73, v73
	v_pk_add_f32 v[66:67], v[66:67], 1.0 op_sel_hi:[1,0] neg_lo:[1,0] neg_hi:[1,0]
	s_nop 0
	v_pk_mul_f32 v[66:67], v[66:67], v[68:69]
	v_exp_f32_e32 v68, v110
	v_cvt_pk_bf16_f32 v105, v66, v67
	v_pk_add_f32 v[66:67], v[112:113], 1.0 op_sel_hi:[1,0] neg_lo:[1,0] neg_hi:[1,0]
	v_exp_f32_e32 v69, v111
	v_pk_mul_f32 v[66:67], v[66:67], v[72:73]
	v_pk_add_f32 v[72:73], v[150:151], v[144:145] neg_lo:[0,1] neg_hi:[0,1]
	v_cvt_pk_bf16_f32 v66, v66, v67
	ds_write2_b32 v71, v105, v66 offset0:160 offset1:240
	v_pk_add_f32 v[66:67], v[150:151], v[142:143] neg_lo:[0,1] neg_hi:[0,1]
	v_exp_f32_e32 v110, v138
	v_exp_f32_e32 v66, v66
	v_exp_f32_e32 v67, v67
	v_exp_f32_e32 v111, v139
	v_exp_f32_e32 v72, v72
	v_exp_f32_e32 v73, v73
	v_pk_add_f32 v[68:69], v[68:69], 1.0 op_sel_hi:[1,0] neg_lo:[1,0] neg_hi:[1,0]
	v_add_u32_e32 v71, 0x5400, v70
	v_pk_mul_f32 v[66:67], v[68:69], v[66:67]
	v_sub_u32_e32 v105, 31, v109
	v_cvt_pk_bf16_f32 v68, v66, v67
	v_pk_add_f32 v[66:67], v[110:111], 1.0 op_sel_hi:[1,0] neg_lo:[1,0] neg_hi:[1,0]
	v_cndmask_b32_e64 v105, v105, v109, s[4:5]
	v_pk_mul_f32 v[66:67], v[66:67], v[72:73]
	v_pk_add_f32 v[72:73], v[150:151], v[148:149] neg_lo:[0,1] neg_hi:[0,1]
	v_cvt_pk_bf16_f32 v69, v66, v67
	v_exp_f32_e32 v66, v106
	v_exp_f32_e32 v67, v107
	ds_write2_b32 v71, v68, v69 offset0:64 offset1:144
	v_pk_add_f32 v[68:69], v[150:151], v[146:147] neg_lo:[0,1] neg_hi:[0,1]
	v_exp_f32_e32 v106, v140
	v_exp_f32_e32 v68, v68
	v_exp_f32_e32 v69, v69
	v_exp_f32_e32 v107, v141
	v_exp_f32_e32 v72, v72
	v_exp_f32_e32 v73, v73
	v_pk_add_f32 v[66:67], v[66:67], 1.0 op_sel_hi:[1,0] neg_lo:[1,0] neg_hi:[1,0]
	s_nop 0
	v_pk_mul_f32 v[66:67], v[66:67], v[68:69]
	s_nop 0
	v_cvt_pk_bf16_f32 v68, v66, v67
	v_pk_add_f32 v[66:67], v[106:107], 1.0 op_sel_hi:[1,0] neg_lo:[1,0] neg_hi:[1,0]
	s_nop 0
	v_pk_mul_f32 v[66:67], v[66:67], v[72:73]
	s_nop 0
	v_cvt_pk_bf16_f32 v66, v66, v67
	v_add_u32_e32 v67, 0x5600, v70
	ds_write2_b32 v67, v68, v66 offset0:96 offset1:176
	v_add_u32_e32 v66, s16, v98
	v_ashrrev_i32_e32 v67, 31, v66
	s_or_b32 s16, s16, s47
	v_lshlrev_b64 v[66:67], 11, v[66:67]
	v_add_u32_e32 v106, s16, v105
	v_sub_u32_e32 v105, 31, v108
	v_lshl_add_u64 v[66:67], s[20:21], 0, v[66:67]
	v_cndmask_b32_e64 v105, v105, v108, s[4:5]
	v_lshl_add_u64 v[66:67], s[38:39], 1, v[66:67]
	v_add_u32_e32 v110, s16, v105
	v_mul_lo_u32 v105, v94, s2
	v_lshl_add_u64 v[70:71], v[86:87], 1, v[66:67]
	v_ashrrev_i32_e32 v111, 31, v110
	v_add_u32_e32 v114, v95, v105
	global_load_dwordx4 v[66:69], v[70:71], off offset:16
	s_nop 0
	global_load_dwordx4 v[70:73], v[70:71], off
	v_lshlrev_b64 v[148:149], 11, v[110:111]
	ds_read_b64_tr_b16 v[110:111], v114 offset:10240
	ds_read_b64_tr_b16 v[112:113], v114 offset:11520
	ds_read_b64_tr_b16 v[124:125], v114 offset:15360
	ds_read_b64_tr_b16 v[126:127], v114 offset:16640
	v_add3_u32 v105, s46, v96, v105
	ds_read_b64_tr_b16 v[128:129], v105
	ds_read_b64_tr_b16 v[130:131], v105 offset:1280
	ds_read_b64_tr_b16 v[132:133], v105 offset:5120
	ds_read_b64_tr_b16 v[134:135], v105 offset:6400
	ds_read_b64_tr_b16 v[136:137], v105 offset:64
	ds_read_b64_tr_b16 v[140:141], v105 offset:128
	ds_read_b64_tr_b16 v[144:145], v105 offset:192
	ds_read_b64_tr_b16 v[138:139], v105 offset:1344
	ds_read_b64_tr_b16 v[142:143], v105 offset:1408
	ds_read_b64_tr_b16 v[146:147], v105 offset:1472
	s_waitcnt lgkmcnt(8)
	v_mfma_f32_32x32x16_bf16 v[2:17], v[128:131], v[110:113], v[2:17]
	v_lshl_add_u64 v[156:157], v[90:91], 0, v[148:149]
	ds_read_b64_tr_b16 v[128:129], v105 offset:5184
	ds_read_b64_tr_b16 v[148:149], v105 offset:5248
	ds_read_b64_tr_b16 v[152:153], v105 offset:5312
	ds_read_b64_tr_b16 v[130:131], v105 offset:6464
	ds_read_b64_tr_b16 v[150:151], v105 offset:6528
	ds_read_b64_tr_b16 v[154:155], v105 offset:6592
	v_sub_u32_e32 v105, 31, v104
	v_cndmask_b32_e64 v105, v105, v104, s[4:5]
	v_ashrrev_i32_e32 v107, 31, v106
	v_lshlrev_b64 v[106:107], 11, v[106:107]
	v_lshl_add_u64 v[106:107], v[90:91], 0, v[106:107]
	s_waitcnt lgkmcnt(8)
	v_mfma_f32_32x32x16_bf16 v[50:65], v[136:139], v[110:113], v[50:65]
	v_mfma_f32_32x32x16_bf16 v[2:17], v[132:135], v[124:127], v[2:17]
	v_add_u32_e32 v132, s16, v105
	v_sub_u32_e32 v105, 31, v103
	v_cndmask_b32_e64 v105, v105, v103, s[4:5]
	v_add_u32_e32 v134, s16, v105
	v_sub_u32_e32 v105, 31, v102
	v_cndmask_b32_e64 v105, v105, v102, s[4:5]
	v_ashrrev_i32_e32 v133, 31, v132
	s_waitcnt lgkmcnt(2)
	v_mfma_f32_32x32x16_bf16 v[50:65], v[128:131], v[124:127], v[50:65]
	v_add_u32_e32 v128, s16, v105
	v_sub_u32_e32 v105, 31, v101
	v_cndmask_b32_e64 v105, v105, v101, s[4:5]
	v_add_u32_e32 v130, s16, v105
	v_sub_u32_e32 v105, 31, v99
	v_cndmask_b32_e64 v105, v105, v99, s[4:5]
	v_add_u32_e32 v136, s16, v105
	v_cndmask_b32_e64 v105, v100, v83, s[4:5]
	v_add_u32_e32 v138, s16, v105
	v_ashrrev_i32_e32 v135, 31, v134
	v_ashrrev_i32_e32 v129, 31, v128
	v_ashrrev_i32_e32 v131, 31, v130
	v_ashrrev_i32_e32 v137, 31, v136
	v_ashrrev_i32_e32 v139, 31, v138
	v_lshlrev_b64 v[132:133], 11, v[132:133]
	v_lshlrev_b64 v[134:135], 11, v[134:135]
	v_lshlrev_b64 v[128:129], 11, v[128:129]
	v_lshlrev_b64 v[130:131], 11, v[130:131]
	v_lshlrev_b64 v[136:137], 11, v[136:137]
	v_lshlrev_b64 v[138:139], 11, v[138:139]
	v_lshl_add_u64 v[132:133], v[90:91], 0, v[132:133]
	v_lshl_add_u64 v[134:135], v[90:91], 0, v[134:135]
	v_lshl_add_u64 v[128:129], v[90:91], 0, v[128:129]
	v_mfma_f32_32x32x16_bf16 v[34:49], v[140:143], v[110:113], v[34:49]
	v_lshl_add_u64 v[130:131], v[90:91], 0, v[130:131]
	v_lshl_add_u64 v[136:137], v[90:91], 0, v[136:137]
	v_lshl_add_u64 v[138:139], v[90:91], 0, v[138:139]
	v_mfma_f32_32x32x16_bf16 v[18:33], v[144:147], v[110:113], v[18:33]
	global_load_dword v105, v[106:107], off
	s_nop 0
	global_load_dword v106, v[156:157], off
	global_load_dword v107, v[132:133], off
	global_load_dword v110, v[134:135], off
	global_load_dword v111, v[128:129], off
	global_load_dword v112, v[130:131], off
	global_load_dword v113, v[136:137], off
	global_load_dword v114, v[138:139], off
	s_waitcnt lgkmcnt(1)
	v_mfma_f32_32x32x16_bf16 v[34:49], v[148:151], v[124:127], v[34:49]
	s_waitcnt lgkmcnt(0)
	v_mfma_f32_32x32x16_bf16 v[18:33], v[152:155], v[124:127], v[18:33]
.LBB0_1201:
	s_and_b64 vcc, exec, s[6:7]
	s_barrier
	s_cbranch_vccnz .LBB0_1203
	s_waitcnt vmcnt(10)
	v_cvt_f32_f16_sdwa v123, v122 dst_sel:DWORD dst_unused:UNUSED_PAD src0_sel:WORD_1
	v_cvt_f32_f16_e32 v122, v122
	s_waitcnt vmcnt(10)
	v_cvt_f32_f16_sdwa v125, v121 dst_sel:DWORD dst_unused:UNUSED_PAD src0_sel:WORD_1
	v_cvt_f32_f16_e32 v124, v121
	s_waitcnt vmcnt(10)
	v_cvt_f32_f16_sdwa v121, v120 dst_sel:DWORD dst_unused:UNUSED_PAD src0_sel:WORD_1
	v_cvt_f32_f16_e32 v120, v120
	s_waitcnt vmcnt(10)
	v_cvt_f32_f16_sdwa v127, v119 dst_sel:DWORD dst_unused:UNUSED_PAD src0_sel:WORD_1
	v_cvt_f32_f16_e32 v126, v119
	v_pk_add_f32 v[128:129], v[122:123], 0 op_sel_hi:[1,0]
	s_waitcnt vmcnt(10)
	v_cvt_f32_f16_sdwa v119, v118 dst_sel:DWORD dst_unused:UNUSED_PAD src0_sel:WORD_1
	v_cvt_f32_f16_e32 v118, v118
	v_pk_add_f32 v[130:131], v[128:129], v[124:125]
	s_waitcnt vmcnt(10)
	v_cvt_f32_f16_sdwa v137, v117 dst_sel:DWORD dst_unused:UNUSED_PAD src0_sel:WORD_1
	v_cvt_f32_f16_e32 v136, v117
	v_pk_add_f32 v[132:133], v[130:131], v[120:121]
	s_waitcnt vmcnt(10)
	v_cvt_f32_f16_sdwa v117, v116 dst_sel:DWORD dst_unused:UNUSED_PAD src0_sel:WORD_1
	v_cvt_f32_f16_e32 v116, v116
	v_pk_add_f32 v[134:135], v[132:133], v[126:127]
	s_waitcnt vmcnt(10)
	v_cvt_f32_f16_sdwa v139, v115 dst_sel:DWORD dst_unused:UNUSED_PAD src0_sel:WORD_1
	v_cvt_f32_f16_e32 v138, v115
	v_pk_add_f32 v[140:141], v[134:135], v[118:119]
	v_lshlrev_b32_e32 v115, 2, v89
	v_pk_add_f32 v[142:143], v[140:141], v[136:137]
	v_exp_f32_e32 v122, v122
	v_pk_add_f32 v[144:145], v[142:143], v[116:117]
	v_exp_f32_e32 v123, v123
	v_pk_add_f32 v[146:147], v[144:145], v[138:139]
	ds_bpermute_b32 v92, v115, v146
	ds_bpermute_b32 v93, v115, v147
	ds_bpermute_b32 v148, v115, v146 offset:64
	ds_bpermute_b32 v149, v115, v147 offset:64
	ds_bpermute_b32 v150, v115, v146 offset:128
	ds_bpermute_b32 v151, v115, v147 offset:128
	ds_bpermute_b32 v152, v115, v146 offset:192
	ds_bpermute_b32 v153, v115, v147 offset:192
	s_waitcnt lgkmcnt(6)
	v_cndmask_b32_e64 v155, 0, v93, s[12:13]
	v_cndmask_b32_e64 v154, 0, v92, s[12:13]
	s_waitcnt lgkmcnt(4)
	v_cndmask_b32_e64 v157, 0, v149, s[10:11]
	v_cndmask_b32_e64 v156, 0, v148, s[10:11]
	v_pk_add_f32 v[154:155], v[154:155], v[156:157]
	s_waitcnt lgkmcnt(2)
	v_cndmask_b32_e64 v157, 0, v151, s[8:9]
	v_cndmask_b32_e64 v156, 0, v150, s[8:9]
	v_pk_add_f32 v[92:93], v[92:93], v[148:149]
	s_waitcnt lgkmcnt(0)
	v_pk_add_f32 v[148:149], v[150:151], v[152:153]
	v_pk_add_f32 v[154:155], v[154:155], v[156:157]
	v_pk_add_f32 v[92:93], v[92:93], v[148:149]
	s_waitcnt vmcnt(10)
	ds_write_b128 v97, v[78:81] offset:10240
	ds_write_b128 v97, v[74:77] offset:10256
	v_pk_add_f32 v[148:149], v[92:93], v[154:155] neg_lo:[0,1] neg_hi:[0,1]
	v_pk_add_f32 v[74:75], v[122:123], 1.0 op_sel_hi:[1,0] neg_lo:[1,0] neg_hi:[1,0]
	v_pk_add_f32 v[148:149], v[84:85], v[148:149]
	v_exp_f32_e32 v76, v124
	v_pk_add_f32 v[128:129], v[148:149], v[128:129] neg_lo:[0,1] neg_hi:[0,1]
	v_exp_f32_e32 v77, v125
	v_exp_f32_e32 v128, v128
	v_exp_f32_e32 v129, v129
	s_movk_i32 s16, 0x140
	v_pk_add_f32 v[76:77], v[76:77], 1.0 op_sel_hi:[1,0] neg_lo:[1,0] neg_hi:[1,0]
	v_mad_u64_u32 v[78:79], s[18:19], v83, s16, v[88:89]
	v_pk_mul_f32 v[74:75], v[74:75], v[128:129]
	s_and_b64 s[18:19], s[4:5], exec
	v_cvt_pk_bf16_f32 v80, v74, v75
	v_pk_add_f32 v[74:75], v[148:149], v[130:131] neg_lo:[0,1] neg_hi:[0,1]
	s_cselect_b32 s2, 32, 0xc0
	v_exp_f32_e32 v74, v74
	v_exp_f32_e32 v75, v75
	s_or_b32 s17, s2, s47
	v_sub_u32_e32 v115, 31, v102
	v_cndmask_b32_e64 v115, v115, v102, s[4:5]
	v_pk_mul_f32 v[74:75], v[76:77], v[74:75]
	v_exp_f32_e32 v76, v120
	v_cvt_pk_bf16_f32 v74, v74, v75
	v_exp_f32_e32 v77, v121
	ds_write2_b32 v78, v80, v74 offset1:80
	v_pk_add_f32 v[74:75], v[148:149], v[132:133] neg_lo:[0,1] neg_hi:[0,1]
	v_pk_add_f32 v[80:81], v[148:149], v[134:135] neg_lo:[0,1] neg_hi:[0,1]
	v_exp_f32_e32 v74, v74
	v_exp_f32_e32 v75, v75
	v_exp_f32_e32 v120, v126
	v_exp_f32_e32 v121, v127
	v_exp_f32_e32 v80, v80
	v_exp_f32_e32 v81, v81
	v_pk_add_f32 v[76:77], v[76:77], 1.0 op_sel_hi:[1,0] neg_lo:[1,0] neg_hi:[1,0]
	v_pk_add_f32 v[84:85], v[84:85], v[92:93]
	v_pk_mul_f32 v[74:75], v[76:77], v[74:75]
	v_exp_f32_e32 v76, v118
	v_cvt_pk_bf16_f32 v79, v74, v75
	v_pk_add_f32 v[74:75], v[120:121], 1.0 op_sel_hi:[1,0] neg_lo:[1,0] neg_hi:[1,0]
	v_exp_f32_e32 v77, v119
	v_pk_mul_f32 v[74:75], v[74:75], v[80:81]
	v_pk_add_f32 v[80:81], v[148:149], v[142:143] neg_lo:[0,1] neg_hi:[0,1]
	v_cvt_pk_bf16_f32 v74, v74, v75
	ds_write2_b32 v78, v79, v74 offset0:160 offset1:240
	v_pk_add_f32 v[74:75], v[148:149], v[140:141] neg_lo:[0,1] neg_hi:[0,1]
	v_exp_f32_e32 v118, v136
	v_exp_f32_e32 v74, v74
	v_exp_f32_e32 v75, v75
	v_exp_f32_e32 v119, v137
	v_exp_f32_e32 v80, v80
	v_exp_f32_e32 v81, v81
	v_pk_add_f32 v[76:77], v[76:77], 1.0 op_sel_hi:[1,0] neg_lo:[1,0] neg_hi:[1,0]
	v_add_u32_e32 v79, 0x400, v78
	v_pk_mul_f32 v[74:75], v[76:77], v[74:75]
	s_nop 0
	v_cvt_pk_bf16_f32 v76, v74, v75
	v_pk_add_f32 v[74:75], v[118:119], 1.0 op_sel_hi:[1,0] neg_lo:[1,0] neg_hi:[1,0]
	s_nop 0
	v_pk_mul_f32 v[74:75], v[74:75], v[80:81]
	v_pk_add_f32 v[80:81], v[148:149], v[146:147] neg_lo:[0,1] neg_hi:[0,1]
	v_cvt_pk_bf16_f32 v77, v74, v75
	v_exp_f32_e32 v74, v116
	v_exp_f32_e32 v75, v117
	ds_write2_b32 v79, v76, v77 offset0:64 offset1:144
	v_pk_add_f32 v[76:77], v[148:149], v[144:145] neg_lo:[0,1] neg_hi:[0,1]
	v_exp_f32_e32 v116, v138
	v_exp_f32_e32 v76, v76
	v_exp_f32_e32 v77, v77
	v_exp_f32_e32 v117, v139
	v_exp_f32_e32 v80, v80
	v_exp_f32_e32 v81, v81
	v_pk_add_f32 v[74:75], v[74:75], 1.0 op_sel_hi:[1,0] neg_lo:[1,0] neg_hi:[1,0]
	s_nop 0
	v_pk_mul_f32 v[74:75], v[74:75], v[76:77]
	s_nop 0
	v_cvt_pk_bf16_f32 v76, v74, v75
	v_pk_add_f32 v[74:75], v[116:117], 1.0 op_sel_hi:[1,0] neg_lo:[1,0] neg_hi:[1,0]
	s_nop 0
	v_pk_mul_f32 v[74:75], v[74:75], v[80:81]
	s_nop 0
	v_cvt_pk_bf16_f32 v74, v74, v75
	v_add_u32_e32 v75, 0x600, v78
	ds_write2_b32 v75, v76, v74 offset0:96 offset1:176
	v_cndmask_b32_e64 v74, v100, v83, s[4:5]
	v_add_u32_e32 v74, s17, v74
	v_ashrrev_i32_e32 v75, 31, v74
	v_lshlrev_b64 v[74:75], 11, v[74:75]
	v_lshl_add_u64 v[144:145], v[90:91], 0, v[74:75]
	v_sub_u32_e32 v74, 31, v99
	v_cndmask_b32_e64 v74, v74, v99, s[4:5]
	v_add_u32_e32 v74, s17, v74
	v_ashrrev_i32_e32 v75, 31, v74
	v_lshlrev_b64 v[74:75], 11, v[74:75]
	v_lshl_add_u64 v[146:147], v[90:91], 0, v[74:75]
	v_sub_u32_e32 v74, 31, v101
	v_cndmask_b32_e64 v74, v74, v101, s[4:5]
	v_add_u32_e32 v74, s17, v74
	v_ashrrev_i32_e32 v75, 31, v74
	v_mul_lo_u32 v78, v94, s16
	v_lshlrev_b64 v[74:75], 11, v[74:75]
	v_add_u32_e32 v79, v95, v78
	v_lshl_add_u64 v[148:149], v[90:91], 0, v[74:75]
	ds_read_b64_tr_b16 v[74:75], v79 offset:30720
	ds_read_b64_tr_b16 v[76:77], v79 offset:32000
	ds_read_b64_tr_b16 v[124:125], v79 offset:35840
	ds_read_b64_tr_b16 v[126:127], v79 offset:37120
	v_add3_u32 v142, s46, v96, v78
	ds_read_b64_tr_b16 v[78:79], v142 offset:20480
	ds_read_b64_tr_b16 v[80:81], v142 offset:21760
	ds_read_b64_tr_b16 v[116:117], v142 offset:25600
	ds_read_b64_tr_b16 v[118:119], v142 offset:26880
	ds_read_b64_tr_b16 v[120:121], v142 offset:20544
	ds_read_b64_tr_b16 v[128:129], v142 offset:20608
	ds_read_b64_tr_b16 v[132:133], v142 offset:20672
	ds_read_b64_tr_b16 v[122:123], v142 offset:21824
	ds_read_b64_tr_b16 v[130:131], v142 offset:21888
	ds_read_b64_tr_b16 v[134:135], v142 offset:21952
	s_waitcnt lgkmcnt(8)
	v_mfma_f32_32x32x16_bf16 v[2:17], v[78:81], v[74:77], v[2:17]
	ds_read_b64_tr_b16 v[78:79], v142 offset:25664
	ds_read_b64_tr_b16 v[136:137], v142 offset:25728
	ds_read_b64_tr_b16 v[140:141], v142 offset:25792
	ds_read_b64_tr_b16 v[80:81], v142 offset:26944
	ds_read_b64_tr_b16 v[138:139], v142 offset:27008
	ds_read_b64_tr_b16 v[142:143], v142 offset:27072
	s_waitcnt lgkmcnt(8)
	v_mfma_f32_32x32x16_bf16 v[50:65], v[120:123], v[74:77], v[50:65]
	v_mfma_f32_32x32x16_bf16 v[2:17], v[116:119], v[124:127], v[2:17]
	v_add_u32_e32 v116, s17, v115
	v_sub_u32_e32 v115, 31, v103
	v_cndmask_b32_e64 v115, v115, v103, s[4:5]
	v_add_u32_e32 v118, s17, v115
	v_ashrrev_i32_e32 v119, 31, v118
	v_sub_u32_e32 v115, 31, v104
	v_lshlrev_b64 v[118:119], 11, v[118:119]
	v_cndmask_b32_e64 v115, v115, v104, s[4:5]
	v_lshl_add_u64 v[150:151], v[90:91], 0, v[118:119]
	v_add_u32_e32 v118, s17, v115
	s_waitcnt lgkmcnt(2)
	v_mfma_f32_32x32x16_bf16 v[50:65], v[78:81], v[124:127], v[50:65]
	v_sub_u32_e32 v80, 31, v108
	v_sub_u32_e32 v115, 31, v109
	v_ashrrev_i32_e32 v119, 31, v118
	v_cndmask_b32_e64 v80, v80, v108, s[4:5]
	v_cndmask_b32_e64 v115, v115, v109, s[4:5]
	v_ashrrev_i32_e32 v117, 31, v116
	v_lshlrev_b64 v[78:79], 11, v[118:119]
	v_add_u32_e32 v80, s17, v80
	v_add_u32_e32 v118, s17, v115
	v_lshlrev_b64 v[116:117], 11, v[116:117]
	v_ashrrev_i32_e32 v81, 31, v80
	v_ashrrev_i32_e32 v119, 31, v118
	v_lshl_add_u64 v[116:117], v[90:91], 0, v[116:117]
	v_lshl_add_u64 v[78:79], v[90:91], 0, v[78:79]
	v_lshlrev_b64 v[80:81], 11, v[80:81]
	v_lshlrev_b64 v[118:119], 11, v[118:119]
	v_mfma_f32_32x32x16_bf16 v[34:49], v[128:131], v[74:77], v[34:49]
	v_lshl_add_u64 v[80:81], v[90:91], 0, v[80:81]
	v_lshl_add_u64 v[128:129], v[90:91], 0, v[118:119]
	global_load_dword v122, v[144:145], off
	global_load_dword v121, v[146:147], off
	global_load_dword v120, v[148:149], off
	global_load_dword v119, v[116:117], off
	global_load_dword v118, v[150:151], off
	s_nop 0
	global_load_dword v117, v[78:79], off
	global_load_dword v116, v[80:81], off
	global_load_dword v115, v[128:129], off
	v_add_u32_e32 v78, s2, v98
	v_ashrrev_i32_e32 v79, 31, v78
	v_lshlrev_b64 v[78:79], 11, v[78:79]
	v_lshl_add_u64 v[78:79], s[20:21], 0, v[78:79]
	v_lshl_add_u64 v[78:79], s[38:39], 1, v[78:79]
	v_lshl_add_u64 v[78:79], v[86:87], 1, v[78:79]
	v_mfma_f32_32x32x16_bf16 v[18:33], v[132:135], v[74:77], v[18:33]
	global_load_dwordx4 v[74:77], v[78:79], off offset:16
	s_nop 0
	global_load_dwordx4 v[78:81], v[78:79], off
	s_waitcnt lgkmcnt(1)
	v_mfma_f32_32x32x16_bf16 v[34:49], v[136:139], v[124:127], v[34:49]
	s_waitcnt lgkmcnt(0)
	v_mfma_f32_32x32x16_bf16 v[18:33], v[140:143], v[124:127], v[18:33]
.LBB0_1203:
	s_and_b64 vcc, exec, s[6:7]
	s_barrier
	s_cbranch_vccnz .LBB0_1205
	s_waitcnt vmcnt(10)
	v_cvt_f32_f16_sdwa v125, v114 dst_sel:DWORD dst_unused:UNUSED_PAD src0_sel:WORD_1
	v_cvt_f32_f16_e32 v124, v114
	v_cvt_f32_f16_sdwa v127, v113 dst_sel:DWORD dst_unused:UNUSED_PAD src0_sel:WORD_1
	v_cvt_f32_f16_e32 v126, v113
	v_cvt_f32_f16_sdwa v113, v112 dst_sel:DWORD dst_unused:UNUSED_PAD src0_sel:WORD_1
	v_cvt_f32_f16_e32 v112, v112
	v_cvt_f32_f16_sdwa v129, v111 dst_sel:DWORD dst_unused:UNUSED_PAD src0_sel:WORD_1
	v_cvt_f32_f16_e32 v128, v111
	v_pk_add_f32 v[130:131], v[124:125], 0 op_sel_hi:[1,0]
	v_cvt_f32_f16_sdwa v111, v110 dst_sel:DWORD dst_unused:UNUSED_PAD src0_sel:WORD_1
	v_cvt_f32_f16_e32 v110, v110
	v_pk_add_f32 v[132:133], v[130:131], v[126:127]
	v_cvt_f32_f16_sdwa v139, v107 dst_sel:DWORD dst_unused:UNUSED_PAD src0_sel:WORD_1
	v_cvt_f32_f16_e32 v138, v107
	v_pk_add_f32 v[134:135], v[132:133], v[112:113]
	v_cvt_f32_f16_sdwa v107, v106 dst_sel:DWORD dst_unused:UNUSED_PAD src0_sel:WORD_1
	v_cvt_f32_f16_e32 v106, v106
	v_pk_add_f32 v[136:137], v[134:135], v[128:129]
	v_cvt_f32_f16_sdwa v141, v105 dst_sel:DWORD dst_unused:UNUSED_PAD src0_sel:WORD_1
	v_cvt_f32_f16_e32 v140, v105
	v_pk_add_f32 v[142:143], v[136:137], v[110:111]
	v_lshlrev_b32_e32 v105, 2, v89
	v_pk_add_f32 v[144:145], v[142:143], v[138:139]
	v_exp_f32_e32 v124, v124
	v_pk_add_f32 v[146:147], v[144:145], v[106:107]
	v_exp_f32_e32 v125, v125
	v_pk_add_f32 v[148:149], v[146:147], v[140:141]
	ds_bpermute_b32 v92, v105, v148
	ds_bpermute_b32 v93, v105, v149
	ds_bpermute_b32 v150, v105, v148 offset:64
	ds_bpermute_b32 v151, v105, v149 offset:64
	ds_bpermute_b32 v152, v105, v148 offset:128
	ds_bpermute_b32 v153, v105, v149 offset:128
	ds_bpermute_b32 v154, v105, v148 offset:192
	ds_bpermute_b32 v155, v105, v149 offset:192
	s_waitcnt lgkmcnt(6)
	v_cndmask_b32_e64 v157, 0, v93, s[12:13]
	v_cndmask_b32_e64 v156, 0, v92, s[12:13]
	s_waitcnt lgkmcnt(4)
	v_cndmask_b32_e64 v159, 0, v151, s[10:11]
	v_cndmask_b32_e64 v158, 0, v150, s[10:11]
	v_pk_add_f32 v[156:157], v[156:157], v[158:159]
	s_waitcnt lgkmcnt(2)
	v_cndmask_b32_e64 v159, 0, v153, s[8:9]
	v_cndmask_b32_e64 v158, 0, v152, s[8:9]
	v_pk_add_f32 v[92:93], v[92:93], v[150:151]
	s_waitcnt lgkmcnt(0)
	v_pk_add_f32 v[150:151], v[152:153], v[154:155]
	v_pk_add_f32 v[156:157], v[156:157], v[158:159]
	v_pk_add_f32 v[92:93], v[92:93], v[150:151]
	ds_write_b128 v97, v[70:73] offset:30720
	ds_write_b128 v97, v[66:69] offset:30736
	v_pk_add_f32 v[150:151], v[92:93], v[156:157] neg_lo:[0,1] neg_hi:[0,1]
	v_pk_add_f32 v[66:67], v[124:125], 1.0 op_sel_hi:[1,0] neg_lo:[1,0] neg_hi:[1,0]
	v_pk_add_f32 v[150:151], v[84:85], v[150:151]
	v_exp_f32_e32 v68, v126
	v_pk_add_f32 v[130:131], v[150:151], v[130:131] neg_lo:[0,1] neg_hi:[0,1]
	v_exp_f32_e32 v69, v127
	v_exp_f32_e32 v130, v130
	v_exp_f32_e32 v131, v131
	s_movk_i32 s2, 0x140
	v_pk_add_f32 v[68:69], v[68:69], 1.0 op_sel_hi:[1,0] neg_lo:[1,0] neg_hi:[1,0]
	v_mad_u64_u32 v[70:71], s[16:17], v83, s2, v[88:89]
	v_pk_mul_f32 v[66:67], v[66:67], v[130:131]
	v_add_u32_e32 v71, 0x5000, v70
	v_cvt_pk_bf16_f32 v72, v66, v67
	v_pk_add_f32 v[66:67], v[150:151], v[132:133] neg_lo:[0,1] neg_hi:[0,1]
	s_and_b64 s[16:17], s[4:5], exec
	v_exp_f32_e32 v66, v66
	v_exp_f32_e32 v67, v67
	s_cselect_b32 s16, 0, 0xe0
	v_cndmask_b32_e64 v100, v100, v83, s[4:5]
	v_pk_add_f32 v[84:85], v[84:85], v[92:93]
	v_pk_mul_f32 v[66:67], v[68:69], v[66:67]
	s_nop 0
	v_cvt_pk_bf16_f32 v68, v66, v67
	v_exp_f32_e32 v66, v112
	v_exp_f32_e32 v67, v113
	ds_write2_b32 v71, v72, v68 offset1:80
	v_pk_add_f32 v[68:69], v[150:151], v[134:135] neg_lo:[0,1] neg_hi:[0,1]
	v_pk_add_f32 v[72:73], v[150:151], v[136:137] neg_lo:[0,1] neg_hi:[0,1]
	v_exp_f32_e32 v68, v68
	v_exp_f32_e32 v69, v69
	v_exp_f32_e32 v112, v128
	v_exp_f32_e32 v113, v129
	v_exp_f32_e32 v72, v72
	v_exp_f32_e32 v73, v73
	v_pk_add_f32 v[66:67], v[66:67], 1.0 op_sel_hi:[1,0] neg_lo:[1,0] neg_hi:[1,0]
	s_nop 0
	v_pk_mul_f32 v[66:67], v[66:67], v[68:69]
	v_exp_f32_e32 v68, v110
	v_cvt_pk_bf16_f32 v105, v66, v67
	v_pk_add_f32 v[66:67], v[112:113], 1.0 op_sel_hi:[1,0] neg_lo:[1,0] neg_hi:[1,0]
	v_exp_f32_e32 v69, v111
	v_pk_mul_f32 v[66:67], v[66:67], v[72:73]
	v_pk_add_f32 v[72:73], v[150:151], v[144:145] neg_lo:[0,1] neg_hi:[0,1]
	v_cvt_pk_bf16_f32 v66, v66, v67
	ds_write2_b32 v71, v105, v66 offset0:160 offset1:240
	v_pk_add_f32 v[66:67], v[150:151], v[142:143] neg_lo:[0,1] neg_hi:[0,1]
	v_exp_f32_e32 v110, v138
	v_exp_f32_e32 v66, v66
	v_exp_f32_e32 v67, v67
	v_exp_f32_e32 v111, v139
	v_exp_f32_e32 v72, v72
	v_exp_f32_e32 v73, v73
	v_pk_add_f32 v[68:69], v[68:69], 1.0 op_sel_hi:[1,0] neg_lo:[1,0] neg_hi:[1,0]
	v_add_u32_e32 v71, 0x5400, v70
	v_pk_mul_f32 v[66:67], v[68:69], v[66:67]
	s_nop 0
	v_cvt_pk_bf16_f32 v68, v66, v67
	v_pk_add_f32 v[66:67], v[110:111], 1.0 op_sel_hi:[1,0] neg_lo:[1,0] neg_hi:[1,0]
	s_nop 0
	v_pk_mul_f32 v[66:67], v[66:67], v[72:73]
	v_pk_add_f32 v[72:73], v[150:151], v[148:149] neg_lo:[0,1] neg_hi:[0,1]
	v_cvt_pk_bf16_f32 v69, v66, v67
	v_exp_f32_e32 v66, v106
	v_exp_f32_e32 v67, v107
	ds_write2_b32 v71, v68, v69 offset0:64 offset1:144
	v_pk_add_f32 v[68:69], v[150:151], v[146:147] neg_lo:[0,1] neg_hi:[0,1]
	v_exp_f32_e32 v106, v140
	v_exp_f32_e32 v68, v68
	v_exp_f32_e32 v69, v69
	v_exp_f32_e32 v107, v141
	v_exp_f32_e32 v72, v72
	v_exp_f32_e32 v73, v73
	v_pk_add_f32 v[66:67], v[66:67], 1.0 op_sel_hi:[1,0] neg_lo:[1,0] neg_hi:[1,0]
	s_nop 0
	v_pk_mul_f32 v[66:67], v[66:67], v[68:69]
	s_nop 0
	v_cvt_pk_bf16_f32 v68, v66, v67
	v_pk_add_f32 v[66:67], v[106:107], 1.0 op_sel_hi:[1,0] neg_lo:[1,0] neg_hi:[1,0]
	s_nop 0
	v_pk_mul_f32 v[66:67], v[66:67], v[72:73]
	s_nop 0
	v_cvt_pk_bf16_f32 v66, v66, v67
	v_add_u32_e32 v67, 0x5600, v70
	ds_write2_b32 v67, v68, v66 offset0:96 offset1:176
	v_add_u32_e32 v66, s16, v98
	v_ashrrev_i32_e32 v67, 31, v66
	v_lshlrev_b64 v[66:67], 11, v[66:67]
	v_sub_u32_e32 v98, 31, v108
	v_lshl_add_u64 v[66:67], s[20:21], 0, v[66:67]
	s_or_b32 s16, s16, s47
	v_cndmask_b32_e64 v98, v98, v108, s[4:5]
	v_lshl_add_u64 v[66:67], s[38:39], 1, v[66:67]
	v_add_u32_e32 v106, s16, v98
	v_mul_lo_u32 v98, v94, s2
	v_lshl_add_u64 v[70:71], v[86:87], 1, v[66:67]
	v_sub_u32_e32 v86, 31, v109
	v_ashrrev_i32_e32 v107, 31, v106
	v_add_u32_e32 v105, v95, v98
	global_load_dwordx4 v[66:69], v[70:71], off offset:16
	s_nop 0
	global_load_dwordx4 v[70:73], v[70:71], off
	v_cndmask_b32_e64 v86, v86, v109, s[4:5]
	v_lshlrev_b64 v[144:145], 11, v[106:107]
	ds_read_b64_tr_b16 v[106:107], v105 offset:10240
	ds_read_b64_tr_b16 v[108:109], v105 offset:11520
	ds_read_b64_tr_b16 v[124:125], v105 offset:15360
	ds_read_b64_tr_b16 v[126:127], v105 offset:16640
	v_add3_u32 v98, s46, v96, v98
	ds_read_b64_tr_b16 v[110:111], v98
	ds_read_b64_tr_b16 v[112:113], v98 offset:1280
	ds_read_b64_tr_b16 v[128:129], v98 offset:5120
	ds_read_b64_tr_b16 v[130:131], v98 offset:6400
	ds_read_b64_tr_b16 v[132:133], v98 offset:64
	ds_read_b64_tr_b16 v[136:137], v98 offset:128
	ds_read_b64_tr_b16 v[140:141], v98 offset:192
	ds_read_b64_tr_b16 v[134:135], v98 offset:1344
	ds_read_b64_tr_b16 v[138:139], v98 offset:1408
	ds_read_b64_tr_b16 v[142:143], v98 offset:1472
	s_waitcnt lgkmcnt(8)
	v_mfma_f32_32x32x16_bf16 v[2:17], v[110:113], v[106:109], v[2:17]
	v_lshl_add_u64 v[152:153], v[90:91], 0, v[144:145]
	ds_read_b64_tr_b16 v[110:111], v98 offset:5184
	ds_read_b64_tr_b16 v[144:145], v98 offset:5248
	ds_read_b64_tr_b16 v[148:149], v98 offset:5312
	ds_read_b64_tr_b16 v[112:113], v98 offset:6464
	ds_read_b64_tr_b16 v[146:147], v98 offset:6528
	ds_read_b64_tr_b16 v[150:151], v98 offset:6592
	v_sub_u32_e32 v98, 31, v104
	v_cndmask_b32_e64 v98, v98, v104, s[4:5]
	v_add_u32_e32 v104, s16, v98
	v_ashrrev_i32_e32 v105, 31, v104
	v_sub_u32_e32 v98, 31, v103
	v_lshlrev_b64 v[104:105], 11, v[104:105]
	v_cndmask_b32_e64 v98, v98, v103, s[4:5]
	s_waitcnt lgkmcnt(12)
	v_mfma_f32_32x32x16_bf16 v[2:17], v[128:131], v[124:127], v[2:17]
	v_lshl_add_u64 v[128:129], v[90:91], 0, v[104:105]
	v_add_u32_e32 v104, s16, v98
	v_sub_u32_e32 v98, 31, v102
	v_cndmask_b32_e64 v98, v98, v102, s[4:5]
	v_ashrrev_i32_e32 v105, 31, v104
	v_add_u32_e32 v102, s16, v98
	v_sub_u32_e32 v98, 31, v101
	s_waitcnt lgkmcnt(8)
	v_mfma_f32_32x32x16_bf16 v[50:65], v[132:135], v[106:109], v[50:65]
	v_lshlrev_b64 v[104:105], 11, v[104:105]
	v_cndmask_b32_e64 v98, v98, v101, s[4:5]
	v_lshl_add_u64 v[130:131], v[90:91], 0, v[104:105]
	v_add_u32_e32 v104, s16, v98
	v_sub_u32_e32 v98, 31, v99
	v_add_u32_e32 v86, s16, v86
	v_cndmask_b32_e64 v98, v98, v99, s[4:5]
	v_ashrrev_i32_e32 v87, 31, v86
	v_ashrrev_i32_e32 v105, 31, v104
	v_add_u32_e32 v98, s16, v98
	v_add_u32_e32 v100, s16, v100
	v_lshlrev_b64 v[86:87], 11, v[86:87]
	v_ashrrev_i32_e32 v103, 31, v102
	v_lshlrev_b64 v[104:105], 11, v[104:105]
	v_ashrrev_i32_e32 v99, 31, v98
	v_ashrrev_i32_e32 v101, 31, v100
	v_lshl_add_u64 v[86:87], v[90:91], 0, v[86:87]
	s_waitcnt lgkmcnt(2)
	v_mfma_f32_32x32x16_bf16 v[50:65], v[110:113], v[124:127], v[50:65]
	v_lshlrev_b64 v[102:103], 11, v[102:103]
	v_lshl_add_u64 v[112:113], v[90:91], 0, v[104:105]
	v_lshlrev_b64 v[98:99], 11, v[98:99]
	v_lshlrev_b64 v[100:101], 11, v[100:101]
	v_lshl_add_u64 v[102:103], v[90:91], 0, v[102:103]
	v_lshl_add_u64 v[98:99], v[90:91], 0, v[98:99]
	v_lshl_add_u64 v[90:91], v[90:91], 0, v[100:101]
	v_mfma_f32_32x32x16_bf16 v[34:49], v[136:139], v[106:109], v[34:49]
	v_mfma_f32_32x32x16_bf16 v[18:33], v[140:143], v[106:109], v[18:33]
	global_load_dword v105, v[86:87], off
	global_load_dword v106, v[152:153], off
	global_load_dword v107, v[128:129], off
	global_load_dword v110, v[130:131], off
	global_load_dword v111, v[102:103], off
	s_nop 0
	global_load_dword v112, v[112:113], off
	s_nop 0
	global_load_dword v113, v[98:99], off
	global_load_dword v114, v[90:91], off
	s_waitcnt lgkmcnt(1)
	v_mfma_f32_32x32x16_bf16 v[34:49], v[144:147], v[124:127], v[34:49]
	s_waitcnt lgkmcnt(0)
	v_mfma_f32_32x32x16_bf16 v[18:33], v[148:151], v[124:127], v[18:33]
.LBB0_1205:
	s_and_b64 vcc, exec, s[6:7]
	s_barrier
	s_cbranch_vccnz .LBB0_1207
	s_waitcnt vmcnt(10)
	v_cvt_f32_f16_sdwa v87, v122 dst_sel:DWORD dst_unused:UNUSED_PAD src0_sel:WORD_1
	v_cvt_f32_f16_e32 v86, v122
	s_waitcnt vmcnt(10)
	v_cvt_f32_f16_sdwa v91, v121 dst_sel:DWORD dst_unused:UNUSED_PAD src0_sel:WORD_1
	v_cvt_f32_f16_e32 v90, v121
	s_waitcnt vmcnt(10)
	v_cvt_f32_f16_sdwa v93, v120 dst_sel:DWORD dst_unused:UNUSED_PAD src0_sel:WORD_1
	v_cvt_f32_f16_e32 v92, v120
	s_waitcnt vmcnt(10)
	v_cvt_f32_f16_sdwa v99, v119 dst_sel:DWORD dst_unused:UNUSED_PAD src0_sel:WORD_1
	v_cvt_f32_f16_e32 v98, v119
	v_pk_add_f32 v[100:101], v[86:87], 0 op_sel_hi:[1,0]
	s_waitcnt vmcnt(10)
	v_cvt_f32_f16_sdwa v119, v118 dst_sel:DWORD dst_unused:UNUSED_PAD src0_sel:WORD_1
	v_cvt_f32_f16_e32 v118, v118
	v_pk_add_f32 v[102:103], v[100:101], v[90:91]
	s_waitcnt vmcnt(10)
	v_cvt_f32_f16_sdwa v123, v117 dst_sel:DWORD dst_unused:UNUSED_PAD src0_sel:WORD_1
	v_cvt_f32_f16_e32 v122, v117
	v_pk_add_f32 v[108:109], v[102:103], v[92:93]
	s_waitcnt vmcnt(10)
	v_cvt_f32_f16_sdwa v117, v116 dst_sel:DWORD dst_unused:UNUSED_PAD src0_sel:WORD_1
	v_cvt_f32_f16_e32 v116, v116
	v_pk_add_f32 v[120:121], v[108:109], v[98:99]
	s_waitcnt vmcnt(10)
	v_cvt_f32_f16_sdwa v125, v115 dst_sel:DWORD dst_unused:UNUSED_PAD src0_sel:WORD_1
	v_cvt_f32_f16_e32 v124, v115
	v_pk_add_f32 v[126:127], v[120:121], v[118:119]
	v_lshlrev_b32_e32 v104, 2, v89
	v_pk_add_f32 v[128:129], v[126:127], v[122:123]
	v_exp_f32_e32 v86, v86
	v_pk_add_f32 v[130:131], v[128:129], v[116:117]
	v_exp_f32_e32 v87, v87
	v_pk_add_f32 v[132:133], v[130:131], v[124:125]
	ds_bpermute_b32 v134, v104, v132
	ds_bpermute_b32 v135, v104, v133
	ds_bpermute_b32 v136, v104, v132 offset:64
	ds_bpermute_b32 v137, v104, v133 offset:64
	ds_bpermute_b32 v138, v104, v132 offset:128
	ds_bpermute_b32 v139, v104, v133 offset:128
	ds_bpermute_b32 v140, v104, v132 offset:192
	ds_bpermute_b32 v141, v104, v133 offset:192
	s_waitcnt lgkmcnt(6)
	v_cndmask_b32_e64 v143, 0, v135, s[12:13]
	v_cndmask_b32_e64 v142, 0, v134, s[12:13]
	s_waitcnt lgkmcnt(4)
	v_cndmask_b32_e64 v145, 0, v137, s[10:11]
	v_cndmask_b32_e64 v144, 0, v136, s[10:11]
	v_pk_add_f32 v[142:143], v[142:143], v[144:145]
	s_waitcnt lgkmcnt(2)
	v_cndmask_b32_e64 v145, 0, v139, s[8:9]
	v_cndmask_b32_e64 v144, 0, v138, s[8:9]
	v_pk_add_f32 v[134:135], v[134:135], v[136:137]
	s_waitcnt lgkmcnt(0)
	v_pk_add_f32 v[136:137], v[138:139], v[140:141]
	v_pk_add_f32 v[142:143], v[142:143], v[144:145]
	v_pk_add_f32 v[136:137], v[134:135], v[136:137]
	s_waitcnt vmcnt(10)
	ds_write_b128 v97, v[78:81] offset:10240
	ds_write_b128 v97, v[74:77] offset:10256
	v_pk_add_f32 v[134:135], v[136:137], v[142:143] neg_lo:[0,1] neg_hi:[0,1]
	v_pk_add_f32 v[74:75], v[86:87], 1.0 op_sel_hi:[1,0] neg_lo:[1,0] neg_hi:[1,0]
	v_pk_add_f32 v[134:135], v[84:85], v[134:135]
	v_exp_f32_e32 v76, v90
	v_pk_add_f32 v[100:101], v[134:135], v[100:101] neg_lo:[0,1] neg_hi:[0,1]
	v_exp_f32_e32 v77, v91
	v_exp_f32_e32 v100, v100
	v_exp_f32_e32 v101, v101
	s_movk_i32 s2, 0x140
	v_pk_add_f32 v[76:77], v[76:77], 1.0 op_sel_hi:[1,0] neg_lo:[1,0] neg_hi:[1,0]
	v_mad_u64_u32 v[78:79], s[16:17], v83, s2, v[88:89]
	v_pk_mul_f32 v[74:75], v[74:75], v[100:101]
	v_exp_f32_e32 v86, v98
	v_cvt_pk_bf16_f32 v80, v74, v75
	v_pk_add_f32 v[74:75], v[134:135], v[102:103] neg_lo:[0,1] neg_hi:[0,1]
	v_exp_f32_e32 v87, v99
	v_exp_f32_e32 v74, v74
	v_exp_f32_e32 v75, v75
	v_pk_add_f32 v[84:85], v[84:85], v[136:137]
	v_pk_mul_f32 v[74:75], v[76:77], v[74:75]
	s_nop 0
	v_cvt_pk_bf16_f32 v74, v74, v75
	v_exp_f32_e32 v76, v92
	v_exp_f32_e32 v77, v93
	ds_write2_b32 v78, v80, v74 offset1:80
	v_pk_add_f32 v[74:75], v[134:135], v[108:109] neg_lo:[0,1] neg_hi:[0,1]
	v_pk_add_f32 v[80:81], v[134:135], v[120:121] neg_lo:[0,1] neg_hi:[0,1]
	v_exp_f32_e32 v74, v74
	v_exp_f32_e32 v75, v75
	v_exp_f32_e32 v80, v80
	v_exp_f32_e32 v81, v81
	v_pk_add_f32 v[76:77], v[76:77], 1.0 op_sel_hi:[1,0] neg_lo:[1,0] neg_hi:[1,0]
	s_nop 0
	v_pk_mul_f32 v[74:75], v[76:77], v[74:75]
	v_exp_f32_e32 v76, v118
	v_cvt_pk_bf16_f32 v79, v74, v75
	v_pk_add_f32 v[74:75], v[86:87], 1.0 op_sel_hi:[1,0] neg_lo:[1,0] neg_hi:[1,0]
	v_exp_f32_e32 v77, v119
	v_pk_mul_f32 v[74:75], v[74:75], v[80:81]
	v_pk_add_f32 v[80:81], v[134:135], v[128:129] neg_lo:[0,1] neg_hi:[0,1]
	v_cvt_pk_bf16_f32 v74, v74, v75
	ds_write2_b32 v78, v79, v74 offset0:160 offset1:240
	v_pk_add_f32 v[74:75], v[134:135], v[126:127] neg_lo:[0,1] neg_hi:[0,1]
	v_exp_f32_e32 v86, v122
	v_exp_f32_e32 v74, v74
	v_exp_f32_e32 v75, v75
	v_exp_f32_e32 v87, v123
	v_exp_f32_e32 v80, v80
	v_exp_f32_e32 v81, v81
	v_pk_add_f32 v[76:77], v[76:77], 1.0 op_sel_hi:[1,0] neg_lo:[1,0] neg_hi:[1,0]
	v_add_u32_e32 v79, 0x400, v78
	v_pk_mul_f32 v[74:75], v[76:77], v[74:75]
	s_nop 0
	v_cvt_pk_bf16_f32 v76, v74, v75
	v_pk_add_f32 v[74:75], v[86:87], 1.0 op_sel_hi:[1,0] neg_lo:[1,0] neg_hi:[1,0]
	v_exp_f32_e32 v86, v124
	v_pk_mul_f32 v[74:75], v[74:75], v[80:81]
	v_pk_add_f32 v[80:81], v[134:135], v[132:133] neg_lo:[0,1] neg_hi:[0,1]
	v_cvt_pk_bf16_f32 v77, v74, v75
	v_exp_f32_e32 v74, v116
	v_exp_f32_e32 v75, v117
	ds_write2_b32 v79, v76, v77 offset0:64 offset1:144
	v_pk_add_f32 v[76:77], v[134:135], v[130:131] neg_lo:[0,1] neg_hi:[0,1]
	v_exp_f32_e32 v87, v125
	v_exp_f32_e32 v76, v76
	v_exp_f32_e32 v77, v77
	v_exp_f32_e32 v80, v80
	v_exp_f32_e32 v81, v81
	v_pk_add_f32 v[74:75], v[74:75], 1.0 op_sel_hi:[1,0] neg_lo:[1,0] neg_hi:[1,0]
	s_nop 0
	v_pk_mul_f32 v[74:75], v[74:75], v[76:77]
	s_nop 0
	v_cvt_pk_bf16_f32 v76, v74, v75
	v_pk_add_f32 v[74:75], v[86:87], 1.0 op_sel_hi:[1,0] neg_lo:[1,0] neg_hi:[1,0]
	s_nop 0
	v_pk_mul_f32 v[74:75], v[74:75], v[80:81]
	s_nop 0
	v_cvt_pk_bf16_f32 v74, v74, v75
	v_add_u32_e32 v75, 0x600, v78
	v_mul_lo_u32 v78, v94, s2
	ds_write2_b32 v75, v76, v74 offset0:96 offset1:176
	v_add_u32_e32 v79, v95, v78
	v_add3_u32 v86, s46, v96, v78
	ds_read_b64_tr_b16 v[74:75], v79 offset:30720
	ds_read_b64_tr_b16 v[76:77], v79 offset:32000
	ds_read_b64_tr_b16 v[80:81], v79 offset:37120
	ds_read_b64_tr_b16 v[90:91], v86 offset:20480
	ds_read_b64_tr_b16 v[92:93], v86 offset:21760
	ds_read_b64_tr_b16 v[98:99], v86 offset:25600
	ds_read_b64_tr_b16 v[100:101], v86 offset:26880
	ds_read_b64_tr_b16 v[116:117], v86 offset:20544
	ds_read_b64_tr_b16 v[120:121], v86 offset:20608
	ds_read_b64_tr_b16 v[124:125], v86 offset:20672
	ds_read_b64_tr_b16 v[118:119], v86 offset:21824
	ds_read_b64_tr_b16 v[122:123], v86 offset:21888
	ds_read_b64_tr_b16 v[126:127], v86 offset:21952
	s_waitcnt lgkmcnt(8)
	v_mfma_f32_32x32x16_bf16 v[2:17], v[90:93], v[74:77], v[2:17]
	ds_read_b64_tr_b16 v[78:79], v79 offset:35840
	ds_read_b64_tr_b16 v[90:91], v86 offset:25664
	ds_read_b64_tr_b16 v[128:129], v86 offset:25728
	ds_read_b64_tr_b16 v[132:133], v86 offset:25792
	ds_read_b64_tr_b16 v[92:93], v86 offset:26944
	ds_read_b64_tr_b16 v[130:131], v86 offset:27008
	ds_read_b64_tr_b16 v[134:135], v86 offset:27072
	s_waitcnt lgkmcnt(9)
	v_mfma_f32_32x32x16_bf16 v[50:65], v[116:119], v[74:77], v[50:65]
	s_waitcnt lgkmcnt(8)
	v_mfma_f32_32x32x16_bf16 v[34:49], v[120:123], v[74:77], v[34:49]
	s_waitcnt lgkmcnt(7)
	v_mfma_f32_32x32x16_bf16 v[18:33], v[124:127], v[74:77], v[18:33]
	s_waitcnt lgkmcnt(6)
	v_mfma_f32_32x32x16_bf16 v[2:17], v[98:101], v[78:81], v[2:17]
	s_waitcnt lgkmcnt(2)
	v_mfma_f32_32x32x16_bf16 v[50:65], v[90:93], v[78:81], v[50:65]
	s_waitcnt lgkmcnt(1)
	v_mfma_f32_32x32x16_bf16 v[34:49], v[128:131], v[78:81], v[34:49]
	s_waitcnt lgkmcnt(0)
	v_mfma_f32_32x32x16_bf16 v[18:33], v[132:135], v[78:81], v[18:33]
